# forget-gate epilogue: log(max(g,1e-30)) without the never-taken denormal pre-scale and inf select
# speedup vs baseline: 1.0055x; 1.0055x over previous
; __device__ __forceinline__ float silu_f(float x) { return x * __builtin_amdgcn_rcpf(1.f + __expf(-x)); }
; __device__ __forceinline__ v4u pack8(const float (&y)[8]) { return (v4u){pk2(y[0], y[1]), pk2(y[2], y[3]), pk2(y[4], y[5]), pk2(y[6], y[7])}; }
;     __device__ __forceinline__ void operator()(const f32x4 (&acc)[2][2][4][2], const pg8::Unit& u, int wr, int wc, int fr, int fq) const {
;     ...
;                         const int row = lrow0 + ai * 128 + m * 16; const size_t off = (size_t)row * 1024 + c;
;                         const f32x4 v0 = acc[ai][bj][m][0] * rs[ai][m], v1 = acc[ai][bj][m][1] * rs[ai][m];
;                         const float v[8] = {v0[0], v0[1], v0[2], v0[3], v1[0], v1[1], v1[2], v1[3]};
;                         float y[8];
;                         if (region == 0) {
; #pragma unroll
;                             for (int j = 0; j < 8; ++j) y[j] = silu_f(v[j]);
;                             *(v4u*)(o0 + off) = pack8(y);
;                         } else if (region == 1) {
;                             float lf[8];
; #pragma unroll
;                             for (int j = 0; j < 8; ++j) {
;                                 const float om = 1.f - lb[j];
;                                 const float fc = fminf(fmaxf(v[j], -80.f), 80.f);
;                                 const float e = __expf(-fc), sg = __builtin_amdgcn_rcpf(1.f + e);
;                                 y[j] = om * e * sg;
;                                 lf[j] = __logf(fmaxf(lb[j] + om * sg, 1e-30f));
;                             }
;                             *(v4u*)(o1 + off) = pack8(y);
;                             *(f32x4*)(of + off) = (f32x4){lf[0], lf[1], lf[2], lf[3]}; *(f32x4*)(of + off + 4) = (f32x4){lf[4], lf[5], lf[6], lf[7]};
.LBB0_918:
	s_waitcnt vmcnt(0)
	v_fmamk_f32 v150, v154, 0x3a800000, v139
	s_cmp_gt_u32 s39, 3
	s_cselect_b64 s[2:3], -1, 0
	v_rsq_f32_e32 v150, v150
	s_cmp_lg_u32 s13, 2
	v_lshlrev_b64 v[166:167], 10, v[178:179]
	s_cselect_b64 s[46:47], -1, 0
	s_nop 0
	v_mov_b32_e32 v168, v150
	v_pk_mul_f32 v[182:183], v[128:129], v[168:169] op_sel_hi:[1,0]
	v_pk_mul_f32 v[128:129], v[122:123], v[168:169] op_sel_hi:[1,0]
	v_cndmask_b32_e64 v122, 0, 1, s[0:1]
	v_or_b32_e32 v180, v166, v198
	v_mov_b32_e32 v181, v167
	v_pk_mul_f32 v[184:185], v[126:127], v[168:169] op_sel_hi:[1,0]
	v_pk_mul_f32 v[126:127], v[124:125], v[168:169] op_sel_hi:[1,0]
	s_mov_b64 s[20:21], -1
	s_and_b64 vcc, exec, s[2:3]
	v_cmp_ne_u32_e64 s[42:43], 1, v122
	s_cbranch_vccz .LBB0_927
	s_and_b64 vcc, exec, s[42:43]
	s_mov_b64 s[0:1], -1
	s_cbranch_vccnz .LBB0_921
	v_max_f32_e32 v122, v184, v184
	s_mov_b32 s20, 0xc2a00000
	v_med3_f32 v122, v122, s20, v195
	v_mul_f32_e32 v122, 0xbfb8aa3b, v122
	v_exp_f32_e32 v122, v122
	v_pk_add_f32 v[150:151], v[176:177], 1.0 op_sel_hi:[1,0] neg_lo:[1,0] neg_hi:[1,0]
	s_mov_b32 s13, 0x3f317217
	s_mov_b32 s15, 0x7f800000
	v_add_f32_e32 v123, 1.0, v122
	v_rcp_f32_e32 v124, v123
	v_max_f32_e32 v123, v185, v185
	v_med3_f32 v123, v123, s20, v195
	v_mul_f32_e32 v123, 0xbfb8aa3b, v123
	v_exp_f32_e32 v123, v123
	v_pk_add_f32 v[152:153], v[174:175], 1.0 op_sel_hi:[1,0] neg_lo:[1,0] neg_hi:[1,0]
	v_pk_add_f32 v[154:155], v[172:173], 1.0 op_sel_hi:[1,0] neg_lo:[1,0] neg_hi:[1,0]
	v_pk_add_f32 v[158:159], v[170:171], 1.0 op_sel_hi:[1,0] neg_lo:[1,0] neg_hi:[1,0]
	v_add_f32_e32 v125, 1.0, v123
	v_rcp_f32_e32 v125, v125
	v_pk_mul_f32 v[122:123], v[122:123], v[150:151]
	s_nop 0
	v_pk_mul_f32 v[186:187], v[124:125], v[122:123]
	v_fma_f32 v122, v124, v150, v176
	v_max_f32_e32 v122, 0xda24260, v122
	s_nop 1
	v_log_f32_e32 v122, v122
	s_nop 0
	v_mul_f32_e32 v123, 0x3f317217, v122
	v_fma_f32 v123, v122, s13, -v123
	v_fmac_f32_e32 v123, 0x3377d1cf, v122
	v_fmac_f32_e32 v123, 0x3f317217, v122
	s_nop 1
	v_mov_b32_e32 v122, v123
	v_fma_f32 v123, v125, v151, v177
	v_max_f32_e32 v123, 0xda24260, v123
	s_nop 1
	v_log_f32_e32 v123, v123
	s_nop 0
	v_mul_f32_e32 v124, 0x3f317217, v123
	v_fma_f32 v124, v123, s13, -v124
	v_fmac_f32_e32 v124, 0x3377d1cf, v123
	v_fmac_f32_e32 v124, 0x3f317217, v123
	s_nop 1
	v_mov_b32_e32 v123, v124
	v_max_f32_e32 v124, v182, v182
	v_med3_f32 v124, v124, s20, v195
	v_mul_f32_e32 v124, 0xbfb8aa3b, v124
	v_exp_f32_e32 v124, v124
	s_nop 0
	v_add_f32_e32 v125, 1.0, v124
	v_rcp_f32_e32 v150, v125
	v_max_f32_e32 v125, v183, v183
	v_med3_f32 v125, v125, s20, v195
	v_mul_f32_e32 v125, 0xbfb8aa3b, v125
	v_exp_f32_e32 v125, v125
	s_nop 0
	v_add_f32_e32 v151, 1.0, v125
	v_rcp_f32_e32 v151, v151
	v_pk_mul_f32 v[124:125], v[124:125], v[152:153]
	s_nop 0
	v_pk_mul_f32 v[188:189], v[150:151], v[124:125]
	v_fma_f32 v124, v150, v152, v174
	v_max_f32_e32 v124, 0xda24260, v124
	s_nop 1
	v_log_f32_e32 v124, v124
	s_nop 0
	v_mul_f32_e32 v125, 0x3f317217, v124
	v_fma_f32 v125, v124, s13, -v125
	v_fmac_f32_e32 v125, 0x3377d1cf, v124
	v_fmac_f32_e32 v125, 0x3f317217, v124
	s_nop 1
	v_mov_b32_e32 v124, v125
	v_fma_f32 v125, v151, v153, v175
	v_max_f32_e32 v125, 0xda24260, v125
	s_nop 1
	v_log_f32_e32 v125, v125
	s_nop 0
	v_mul_f32_e32 v150, 0x3f317217, v125
	v_fma_f32 v150, v125, s13, -v150
	v_fmac_f32_e32 v150, 0x3377d1cf, v125
	v_fmac_f32_e32 v150, 0x3f317217, v125
	s_nop 1
	v_mov_b32_e32 v125, v150
	v_max_f32_e32 v150, v128, v128
	v_med3_f32 v150, v150, s20, v195
	v_mul_f32_e32 v150, 0xbfb8aa3b, v150
	v_exp_f32_e32 v150, v150
	s_nop 0
	v_add_f32_e32 v151, 1.0, v150
	v_rcp_f32_e32 v152, v151
	v_max_f32_e32 v151, v129, v129
	v_med3_f32 v151, v151, s20, v195
	v_mul_f32_e32 v151, 0xbfb8aa3b, v151
	v_exp_f32_e32 v151, v151
	s_nop 0
	v_add_f32_e32 v153, 1.0, v151
	v_rcp_f32_e32 v153, v153
	v_pk_mul_f32 v[150:151], v[150:151], v[154:155]
	s_nop 0
	v_pk_mul_f32 v[156:157], v[152:153], v[150:151]
	v_fma_f32 v150, v152, v154, v172
	v_max_f32_e32 v150, 0xda24260, v150
	v_cvt_pk_bf16_f32 v156, v156, v157
	s_nop 0
	v_log_f32_e32 v150, v150
	s_nop 0
	v_mul_f32_e32 v151, 0x3f317217, v150
	v_fma_f32 v151, v150, s13, -v151
	v_fmac_f32_e32 v151, 0x3377d1cf, v150
	v_fmac_f32_e32 v151, 0x3f317217, v150
	s_nop 1
	v_mov_b32_e32 v150, v151
	v_fma_f32 v151, v153, v155, v173
	v_max_f32_e32 v151, 0xda24260, v151
	s_nop 1
	v_log_f32_e32 v151, v151
	s_nop 0
	v_mul_f32_e32 v152, 0x3f317217, v151
	v_fma_f32 v152, v151, s13, -v152
	v_fmac_f32_e32 v152, 0x3377d1cf, v151
	v_fmac_f32_e32 v152, 0x3f317217, v151
	s_nop 1
	v_mov_b32_e32 v151, v152
	v_max_f32_e32 v152, v126, v126
	v_med3_f32 v152, v152, s20, v195
	v_mul_f32_e32 v152, 0xbfb8aa3b, v152
	v_exp_f32_e32 v152, v152
	s_nop 0
	v_add_f32_e32 v153, 1.0, v152
	v_rcp_f32_e32 v154, v153
	v_max_f32_e32 v153, v127, v127
	v_med3_f32 v153, v153, s20, v195
	v_mul_f32_e32 v153, 0xbfb8aa3b, v153
	v_exp_f32_e32 v153, v153
	s_nop 0
	v_add_f32_e32 v155, 1.0, v153
	v_rcp_f32_e32 v155, v155
	v_pk_mul_f32 v[152:153], v[152:153], v[158:159]
	s_nop 0
	v_pk_mul_f32 v[206:207], v[154:155], v[152:153]
	v_fma_f32 v152, v154, v158, v170
	v_max_f32_e32 v152, 0xda24260, v152
	v_cvt_pk_bf16_f32 v157, v206, v207
	s_nop 0
	v_log_f32_e32 v152, v152
	s_nop 0
	v_mul_f32_e32 v153, 0x3f317217, v152
	v_fma_f32 v153, v152, s13, -v153
	v_fmac_f32_e32 v153, 0x3377d1cf, v152
	v_fmac_f32_e32 v153, 0x3f317217, v152
	s_nop 1
	v_mov_b32_e32 v152, v153
	v_fma_f32 v153, v155, v159, v171
	v_max_f32_e32 v153, 0xda24260, v153
	v_cvt_pk_bf16_f32 v155, v188, v189
	s_nop 0
	v_log_f32_e32 v153, v153
	s_nop 0
	v_mul_f32_e32 v154, 0x3f317217, v153
	v_fma_f32 v154, v153, s13, -v154
	v_fmac_f32_e32 v154, 0x3377d1cf, v153
	v_fmac_f32_e32 v154, 0x3f317217, v153
	s_nop 1
	v_mov_b32_e32 v153, v154
	v_readlane_b32 s0, v253, 0
	v_readlane_b32 s1, v253, 1
	v_lshl_add_u64 v[158:159], v[180:181], 1, s[0:1]
	v_readlane_b32 s0, v253, 15
	v_cvt_pk_bf16_f32 v154, v186, v187
	v_readlane_b32 s1, v253, 16
	global_store_dwordx4 v[158:159], v[154:157], off
	s_nop 1
	v_lshl_add_u64 v[154:155], v[180:181], 2, s[0:1]
	s_mov_b64 s[0:1], 0
	global_store_dwordx4 v[154:155], v[122:125], off
	global_store_dwordx4 v[154:155], v[150:153], off offset:16

; __device__ __forceinline__ float silu_f(float x) { return x * __builtin_amdgcn_rcpf(1.f + __expf(-x)); }
; __device__ __forceinline__ v4u pack8(const float (&y)[8]) { return (v4u){pk2(y[0], y[1]), pk2(y[2], y[3]), pk2(y[4], y[5]), pk2(y[6], y[7])}; }
;     __device__ __forceinline__ void operator()(const f32x4 (&acc)[2][2][4][2], const pg8::Unit& u, int wr, int wc, int fr, int fq) const {
;     ...
;                         const int row = lrow0 + ai * 128 + m * 16; const size_t off = (size_t)row * 1024 + c;
;                         const f32x4 v0 = acc[ai][bj][m][0] * rs[ai][m], v1 = acc[ai][bj][m][1] * rs[ai][m];
;                         const float v[8] = {v0[0], v0[1], v0[2], v0[3], v1[0], v1[1], v1[2], v1[3]};
;                         float y[8];
;                         if (region == 0) {
; #pragma unroll
;                             for (int j = 0; j < 8; ++j) y[j] = silu_f(v[j]);
;                             *(v4u*)(o0 + off) = pack8(y);
;                         } else if (region == 1) {
;                             float lf[8];
; #pragma unroll
;                             for (int j = 0; j < 8; ++j) {
;                                 const float om = 1.f - lb[j];
;                                 const float fc = fminf(fmaxf(v[j], -80.f), 80.f);
;                                 const float e = __expf(-fc), sg = __builtin_amdgcn_rcpf(1.f + e);
;                                 y[j] = om * e * sg;
;                                 lf[j] = __logf(fmaxf(lb[j] + om * sg, 1e-30f));
;                             }
;                             *(v4u*)(o1 + off) = pack8(y);
;                             *(f32x4*)(of + off) = (f32x4){lf[0], lf[1], lf[2], lf[3]}; *(f32x4*)(of + off + 4) = (f32x4){lf[4], lf[5], lf[6], lf[7]};
.LBB0_929:
	s_nop 1
	v_fmamk_f32 v122, v205, 0x3a800000, v139
	s_mov_b64 s[0:1], -1
	s_mov_b32 s20, s85
	v_rsq_f32_e32 v124, v122
	v_or_b32_e32 v122, 16, v178
	v_ashrrev_i32_e32 v123, 31, v122
	v_lshlrev_b64 v[122:123], 10, v[122:123]
	s_nop 0
	v_pk_mul_f32 v[128:129], v[120:121], v[124:125] op_sel_hi:[1,0]
	v_pk_mul_f32 v[120:121], v[114:115], v[124:125] op_sel_hi:[1,0]
	v_cndmask_b32_e64 v114, 0, 1, s[2:3]
	s_andn2_b64 vcc, exec, s[2:3]
	v_readlane_b32 s2, v253, 15
	v_or_b32_e32 v126, v122, v198
	v_mov_b32_e32 v127, v123
	v_pk_mul_f32 v[180:181], v[118:119], v[124:125] op_sel_hi:[1,0]
	v_pk_mul_f32 v[118:119], v[116:117], v[124:125] op_sel_hi:[1,0]
	v_cmp_ne_u32_e64 s[44:45], 1, v114
	v_readlane_b32 s3, v253, 16
	s_mov_b32 s21, 0x100000
	s_cbranch_vccnz .LBB0_938
	s_and_b64 vcc, exec, s[42:43]
	s_cbranch_vccnz .LBB0_932
	v_max_f32_e32 v114, v180, v180
	s_mov_b32 s39, 0xc2a00000
	v_med3_f32 v114, v114, s39, v195
	v_mul_f32_e32 v114, 0xbfb8aa3b, v114
	v_exp_f32_e32 v114, v114
	v_pk_add_f32 v[150:151], v[176:177], 1.0 op_sel_hi:[1,0] neg_lo:[1,0] neg_hi:[1,0]
	s_mov_b32 s13, 0x3f317217
	s_mov_b32 s15, 0x7f800000
	v_add_f32_e32 v115, 1.0, v114
	v_rcp_f32_e32 v116, v115
	v_max_f32_e32 v115, v181, v181
	v_med3_f32 v115, v115, s39, v195
	v_mul_f32_e32 v115, 0xbfb8aa3b, v115
	v_exp_f32_e32 v115, v115
	v_pk_add_f32 v[152:153], v[174:175], 1.0 op_sel_hi:[1,0] neg_lo:[1,0] neg_hi:[1,0]
	v_pk_add_f32 v[154:155], v[172:173], 1.0 op_sel_hi:[1,0] neg_lo:[1,0] neg_hi:[1,0]
	v_pk_add_f32 v[158:159], v[170:171], 1.0 op_sel_hi:[1,0] neg_lo:[1,0] neg_hi:[1,0]
	v_add_f32_e32 v117, 1.0, v115
	v_rcp_f32_e32 v117, v117
	v_pk_mul_f32 v[114:115], v[114:115], v[150:151]
	s_nop 0
	v_pk_mul_f32 v[182:183], v[116:117], v[114:115]
	v_fma_f32 v114, v116, v150, v176
	v_max_f32_e32 v114, 0xda24260, v114
	s_nop 1
	v_log_f32_e32 v114, v114
	s_nop 0
	v_mul_f32_e32 v115, 0x3f317217, v114
	v_fma_f32 v115, v114, s13, -v115
	v_fmac_f32_e32 v115, 0x3377d1cf, v114
	v_fmac_f32_e32 v115, 0x3f317217, v114
	s_nop 1
	v_mov_b32_e32 v114, v115
	v_fma_f32 v115, v117, v151, v177
	v_max_f32_e32 v115, 0xda24260, v115
	s_nop 1
	v_log_f32_e32 v115, v115
	s_nop 0
	v_mul_f32_e32 v116, 0x3f317217, v115
	v_fma_f32 v116, v115, s13, -v116
	v_fmac_f32_e32 v116, 0x3377d1cf, v115
	v_fmac_f32_e32 v116, 0x3f317217, v115
	s_nop 1
	v_mov_b32_e32 v115, v116
	v_max_f32_e32 v116, v128, v128
	v_med3_f32 v116, v116, s39, v195
	v_mul_f32_e32 v116, 0xbfb8aa3b, v116
	v_exp_f32_e32 v116, v116
	s_nop 0
	v_add_f32_e32 v117, 1.0, v116
	v_rcp_f32_e32 v150, v117
	v_max_f32_e32 v117, v129, v129
	v_med3_f32 v117, v117, s39, v195
	v_mul_f32_e32 v117, 0xbfb8aa3b, v117
	v_exp_f32_e32 v117, v117
	s_nop 0
	v_add_f32_e32 v125, 1.0, v117
	v_rcp_f32_e32 v151, v125
	v_pk_mul_f32 v[116:117], v[116:117], v[152:153]
	s_nop 0
	v_pk_mul_f32 v[184:185], v[150:151], v[116:117]
	v_fma_f32 v116, v150, v152, v174
	v_max_f32_e32 v116, 0xda24260, v116
	s_nop 1
	v_log_f32_e32 v116, v116
	s_nop 0
	v_mul_f32_e32 v117, 0x3f317217, v116
	v_fma_f32 v117, v116, s13, -v117
	v_fmac_f32_e32 v117, 0x3377d1cf, v116
	v_fmac_f32_e32 v117, 0x3f317217, v116
	s_nop 1
	v_mov_b32_e32 v116, v117
	v_fma_f32 v117, v151, v153, v175
	v_max_f32_e32 v117, 0xda24260, v117
	s_nop 1
	v_log_f32_e32 v117, v117
	s_nop 0
	v_mul_f32_e32 v125, 0x3f317217, v117
	v_fma_f32 v125, v117, s13, -v125
	v_fmac_f32_e32 v125, 0x3377d1cf, v117
	v_fmac_f32_e32 v125, 0x3f317217, v117
	s_nop 1
	v_mov_b32_e32 v117, v125
	v_max_f32_e32 v125, v120, v120
	v_med3_f32 v125, v125, s39, v195
	v_mul_f32_e32 v125, 0xbfb8aa3b, v125
	v_exp_f32_e32 v150, v125
	s_nop 0
	v_add_f32_e32 v125, 1.0, v150
	v_rcp_f32_e32 v152, v125
	v_max_f32_e32 v125, v121, v121
	v_med3_f32 v125, v125, s39, v195
	v_mul_f32_e32 v125, 0xbfb8aa3b, v125
	v_exp_f32_e32 v151, v125
	s_nop 0
	v_add_f32_e32 v125, 1.0, v151
	v_rcp_f32_e32 v153, v125
	v_fma_f32 v125, v152, v154, v172
	v_max_f32_e32 v125, 0xda24260, v125
	v_pk_mul_f32 v[150:151], v[150:151], v[154:155]
	v_pk_mul_f32 v[156:157], v[152:153], v[150:151]
	s_nop 0
	v_log_f32_e32 v125, v125
	v_cvt_pk_bf16_f32 v156, v156, v157
	v_mul_f32_e32 v150, 0x3f317217, v125
	v_fma_f32 v150, v125, s13, -v150
	v_fmac_f32_e32 v150, 0x3377d1cf, v125
	v_fmac_f32_e32 v150, 0x3f317217, v125
	s_nop 1
	v_mov_b32_e32 v125, v150
	v_mov_b32_e32 v150, v125
	v_fma_f32 v125, v153, v155, v173
	v_max_f32_e32 v125, 0xda24260, v125
	s_nop 1
	v_log_f32_e32 v125, v125
	s_nop 0
	v_mul_f32_e32 v151, 0x3f317217, v125
	v_fma_f32 v151, v125, s13, -v151
	v_fmac_f32_e32 v151, 0x3377d1cf, v125
	v_fmac_f32_e32 v151, 0x3f317217, v125
	s_nop 1
	v_mov_b32_e32 v125, v151
	v_mov_b32_e32 v151, v125
	v_max_f32_e32 v125, v118, v118
	v_med3_f32 v125, v125, s39, v195
	v_mul_f32_e32 v125, 0xbfb8aa3b, v125
	v_exp_f32_e32 v152, v125
	s_nop 0
	v_add_f32_e32 v125, 1.0, v152
	v_rcp_f32_e32 v154, v125
	v_max_f32_e32 v125, v119, v119
	v_med3_f32 v125, v125, s39, v195
	v_mul_f32_e32 v125, 0xbfb8aa3b, v125
	v_exp_f32_e32 v153, v125
	s_nop 0
	v_add_f32_e32 v125, 1.0, v153
	v_rcp_f32_e32 v155, v125
	v_fma_f32 v125, v154, v158, v170
	v_max_f32_e32 v125, 0xda24260, v125
	v_pk_mul_f32 v[152:153], v[152:153], v[158:159]
	v_pk_mul_f32 v[186:187], v[154:155], v[152:153]
	v_cvt_pk_bf16_f32 v154, v182, v183
	v_log_f32_e32 v125, v125
	v_cvt_pk_bf16_f32 v157, v186, v187
	v_mul_f32_e32 v152, 0x3f317217, v125
	v_fma_f32 v152, v125, s13, -v152
	v_fmac_f32_e32 v152, 0x3377d1cf, v125
	v_fmac_f32_e32 v152, 0x3f317217, v125
	s_nop 1
	v_mov_b32_e32 v125, v152
	v_mov_b32_e32 v152, v125
	v_fma_f32 v125, v155, v159, v171
	v_max_f32_e32 v125, 0xda24260, v125
	v_cvt_pk_bf16_f32 v155, v184, v185
	s_nop 0
	v_log_f32_e32 v125, v125
	s_nop 0
	v_mul_f32_e32 v153, 0x3f317217, v125
	v_fma_f32 v153, v125, s13, -v153
	v_fmac_f32_e32 v153, 0x3377d1cf, v125
	v_fmac_f32_e32 v153, 0x3f317217, v125
	s_nop 1
	v_mov_b32_e32 v125, v153
	v_readlane_b32 s0, v253, 0
	v_readlane_b32 s1, v253, 1
	v_mov_b32_e32 v153, v125
	v_lshl_add_u64 v[158:159], v[126:127], 1, s[0:1]
	global_store_dwordx4 v[158:159], v[154:157], off
	s_mov_b64 s[0:1], 0
	s_nop 0
	v_lshl_add_u64 v[154:155], v[126:127], 2, s[2:3]
	global_store_dwordx4 v[154:155], v[114:117], off
	global_store_dwordx4 v[154:155], v[150:153], off offset:16

; __device__ __forceinline__ float silu_f(float x) { return x * __builtin_amdgcn_rcpf(1.f + __expf(-x)); }
; __device__ __forceinline__ v4u pack8(const float (&y)[8]) { return (v4u){pk2(y[0], y[1]), pk2(y[2], y[3]), pk2(y[4], y[5]), pk2(y[6], y[7])}; }
;     __device__ __forceinline__ void operator()(const f32x4 (&acc)[2][2][4][2], const pg8::Unit& u, int wr, int wc, int fr, int fq) const {
;     ...
;                         const int row = lrow0 + ai * 128 + m * 16; const size_t off = (size_t)row * 1024 + c;
;                         const f32x4 v0 = acc[ai][bj][m][0] * rs[ai][m], v1 = acc[ai][bj][m][1] * rs[ai][m];
;                         const float v[8] = {v0[0], v0[1], v0[2], v0[3], v1[0], v1[1], v1[2], v1[3]};
;                         float y[8];
;                         if (region == 0) {
; #pragma unroll
;                             for (int j = 0; j < 8; ++j) y[j] = silu_f(v[j]);
;                             *(v4u*)(o0 + off) = pack8(y);
;                         } else if (region == 1) {
;                             float lf[8];
; #pragma unroll
;                             for (int j = 0; j < 8; ++j) {
;                                 const float om = 1.f - lb[j];
;                                 const float fc = fminf(fmaxf(v[j], -80.f), 80.f);
;                                 const float e = __expf(-fc), sg = __builtin_amdgcn_rcpf(1.f + e);
;                                 y[j] = om * e * sg;
;                                 lf[j] = __logf(fmaxf(lb[j] + om * sg, 1e-30f));
;                             }
;                             *(v4u*)(o1 + off) = pack8(y);
;                             *(f32x4*)(of + off) = (f32x4){lf[0], lf[1], lf[2], lf[3]}; *(f32x4*)(of + off + 4) = (f32x4){lf[4], lf[5], lf[6], lf[7]};
.LBB0_940:
	s_nop 1
	v_fmamk_f32 v114, v204, 0x3a800000, v139
	s_mov_b64 s[0:1], -1
	s_nop 0
	v_rsq_f32_e32 v116, v114
	v_or_b32_e32 v114, 32, v178
	v_ashrrev_i32_e32 v115, 31, v114
	v_lshlrev_b64 v[114:115], 10, v[114:115]
	s_nop 0
	v_or_b32_e32 v118, v114, v198
	v_mov_b32_e32 v119, v115
	v_pk_mul_f32 v[120:121], v[112:113], v[116:117] op_sel_hi:[1,0]
	v_pk_mul_f32 v[126:127], v[110:111], v[116:117] op_sel_hi:[1,0]
	v_pk_mul_f32 v[110:111], v[108:109], v[116:117] op_sel_hi:[1,0]
	v_pk_mul_f32 v[112:113], v[106:107], v[116:117] op_sel_hi:[1,0]
	s_and_b64 vcc, exec, s[44:45]
	s_cbranch_vccnz .LBB0_949
	s_and_b64 vcc, exec, s[42:43]
	s_cbranch_vccnz .LBB0_943
	v_max_f32_e32 v106, v126, v126
	s_mov_b32 s39, 0xc2a00000
	v_med3_f32 v106, v106, s39, v195
	v_mul_f32_e32 v106, 0xbfb8aa3b, v106
	v_exp_f32_e32 v106, v106
	v_pk_add_f32 v[150:151], v[176:177], 1.0 op_sel_hi:[1,0] neg_lo:[1,0] neg_hi:[1,0]
	s_mov_b32 s13, 0x3f317217
	s_mov_b32 s15, 0x7f800000
	v_add_f32_e32 v107, 1.0, v106
	v_rcp_f32_e32 v108, v107
	v_max_f32_e32 v107, v127, v127
	v_med3_f32 v107, v107, s39, v195
	v_mul_f32_e32 v107, 0xbfb8aa3b, v107
	v_exp_f32_e32 v107, v107
	v_pk_add_f32 v[152:153], v[174:175], 1.0 op_sel_hi:[1,0] neg_lo:[1,0] neg_hi:[1,0]
	v_pk_add_f32 v[154:155], v[172:173], 1.0 op_sel_hi:[1,0] neg_lo:[1,0] neg_hi:[1,0]
	v_pk_add_f32 v[158:159], v[170:171], 1.0 op_sel_hi:[1,0] neg_lo:[1,0] neg_hi:[1,0]
	v_add_f32_e32 v109, 1.0, v107
	v_rcp_f32_e32 v109, v109
	v_pk_mul_f32 v[106:107], v[106:107], v[150:151]
	s_nop 0
	v_pk_mul_f32 v[128:129], v[108:109], v[106:107]
	v_fma_f32 v106, v108, v150, v176
	v_max_f32_e32 v106, 0xda24260, v106
	s_nop 1
	v_log_f32_e32 v106, v106
	s_nop 0
	v_mul_f32_e32 v107, 0x3f317217, v106
	v_fma_f32 v107, v106, s13, -v107
	v_fmac_f32_e32 v107, 0x3377d1cf, v106
	v_fmac_f32_e32 v107, 0x3f317217, v106
	s_nop 1
	v_mov_b32_e32 v106, v107
	v_fma_f32 v107, v109, v151, v177
	v_max_f32_e32 v107, 0xda24260, v107
	s_nop 1
	v_log_f32_e32 v107, v107
	s_nop 0
	v_mul_f32_e32 v108, 0x3f317217, v107
	v_fma_f32 v108, v107, s13, -v108
	v_fmac_f32_e32 v108, 0x3377d1cf, v107
	v_fmac_f32_e32 v108, 0x3f317217, v107
	s_nop 1
	v_mov_b32_e32 v107, v108
	v_max_f32_e32 v108, v120, v120
	v_med3_f32 v108, v108, s39, v195
	v_mul_f32_e32 v108, 0xbfb8aa3b, v108
	v_exp_f32_e32 v108, v108
	s_nop 0
	v_add_f32_e32 v109, 1.0, v108
	v_rcp_f32_e32 v150, v109
	v_max_f32_e32 v109, v121, v121
	v_med3_f32 v109, v109, s39, v195
	v_mul_f32_e32 v109, 0xbfb8aa3b, v109
	v_exp_f32_e32 v109, v109
	s_nop 0
	v_add_f32_e32 v117, 1.0, v109
	v_rcp_f32_e32 v151, v117
	v_pk_mul_f32 v[108:109], v[108:109], v[152:153]
	s_nop 0
	v_pk_mul_f32 v[180:181], v[150:151], v[108:109]
	v_fma_f32 v108, v150, v152, v174
	v_max_f32_e32 v108, 0xda24260, v108
	s_nop 1
	v_log_f32_e32 v108, v108
	s_nop 0
	v_mul_f32_e32 v109, 0x3f317217, v108
	v_fma_f32 v109, v108, s13, -v109
	v_fmac_f32_e32 v109, 0x3377d1cf, v108
	v_fmac_f32_e32 v109, 0x3f317217, v108
	s_nop 1
	v_mov_b32_e32 v108, v109
	v_fma_f32 v109, v151, v153, v175
	v_max_f32_e32 v109, 0xda24260, v109
	s_nop 1
	v_log_f32_e32 v109, v109
	s_nop 0
	v_mul_f32_e32 v117, 0x3f317217, v109
	v_fma_f32 v117, v109, s13, -v117
	v_fmac_f32_e32 v117, 0x3377d1cf, v109
	v_fmac_f32_e32 v117, 0x3f317217, v109
	s_nop 1
	v_mov_b32_e32 v109, v117
	v_max_f32_e32 v117, v112, v112
	v_med3_f32 v117, v117, s39, v195
	v_mul_f32_e32 v117, 0xbfb8aa3b, v117
	v_exp_f32_e32 v150, v117
	s_nop 0
	v_add_f32_e32 v117, 1.0, v150
	v_rcp_f32_e32 v152, v117
	v_max_f32_e32 v117, v113, v113
	v_med3_f32 v117, v117, s39, v195
	v_mul_f32_e32 v117, 0xbfb8aa3b, v117
	v_exp_f32_e32 v151, v117
	s_nop 0
	v_add_f32_e32 v117, 1.0, v151
	v_rcp_f32_e32 v153, v117
	v_fma_f32 v117, v152, v154, v172
	v_max_f32_e32 v117, 0xda24260, v117
	v_pk_mul_f32 v[150:151], v[150:151], v[154:155]
	s_nop 0
	v_log_f32_e32 v117, v117
	v_pk_mul_f32 v[156:157], v[152:153], v[150:151]
	v_mul_f32_e32 v125, 0x3f317217, v117
	v_fma_f32 v125, v117, s13, -v125
	v_fmac_f32_e32 v125, 0x3377d1cf, v117
	v_fmac_f32_e32 v125, 0x3f317217, v117
	v_cvt_pk_bf16_f32 v156, v156, v157
	s_nop 0
	v_mov_b32_e32 v117, v125
	v_mov_b32_e32 v150, v117
	v_fma_f32 v117, v153, v155, v173
	v_max_f32_e32 v117, 0xda24260, v117
	s_nop 1
	v_log_f32_e32 v117, v117
	s_nop 0
	v_mul_f32_e32 v125, 0x3f317217, v117
	v_fma_f32 v125, v117, s13, -v125
	v_fmac_f32_e32 v125, 0x3377d1cf, v117
	v_fmac_f32_e32 v125, 0x3f317217, v117
	s_nop 1
	v_mov_b32_e32 v117, v125
	v_mov_b32_e32 v151, v117
	v_max_f32_e32 v117, v110, v110
	v_med3_f32 v117, v117, s39, v195
	v_mul_f32_e32 v117, 0xbfb8aa3b, v117
	v_exp_f32_e32 v152, v117
	s_nop 0
	v_add_f32_e32 v117, 1.0, v152
	v_rcp_f32_e32 v154, v117
	v_max_f32_e32 v117, v111, v111
	v_med3_f32 v117, v117, s39, v195
	v_mul_f32_e32 v117, 0xbfb8aa3b, v117
	v_exp_f32_e32 v153, v117
	s_nop 0
	v_add_f32_e32 v117, 1.0, v153
	v_rcp_f32_e32 v155, v117
	v_fma_f32 v117, v154, v158, v170
	v_max_f32_e32 v117, 0xda24260, v117
	v_pk_mul_f32 v[152:153], v[152:153], v[158:159]
	s_nop 0
	v_log_f32_e32 v117, v117
	v_pk_mul_f32 v[182:183], v[154:155], v[152:153]
	v_cvt_pk_bf16_f32 v154, v128, v129
	v_cvt_pk_bf16_f32 v157, v182, v183
	v_mul_f32_e32 v125, 0x3f317217, v117
	v_fma_f32 v125, v117, s13, -v125
	v_fmac_f32_e32 v125, 0x3377d1cf, v117
	v_fmac_f32_e32 v125, 0x3f317217, v117
	s_nop 1
	v_mov_b32_e32 v117, v125
	v_mov_b32_e32 v152, v117
	v_fma_f32 v117, v155, v159, v171
	v_max_f32_e32 v117, 0xda24260, v117
	v_cvt_pk_bf16_f32 v155, v180, v181
	s_nop 0
	v_log_f32_e32 v117, v117
	s_nop 0
	v_mul_f32_e32 v125, 0x3f317217, v117
	v_fma_f32 v125, v117, s13, -v125
	v_fmac_f32_e32 v125, 0x3377d1cf, v117
	v_fmac_f32_e32 v125, 0x3f317217, v117
	s_nop 1
	v_mov_b32_e32 v117, v125
	v_readlane_b32 s0, v253, 0
	v_readlane_b32 s1, v253, 1
	v_mov_b32_e32 v153, v117
	v_lshl_add_u64 v[128:129], v[118:119], 1, s[0:1]
	global_store_dwordx4 v[128:129], v[154:157], off
	v_lshl_add_u64 v[128:129], v[118:119], 2, s[2:3]
	s_mov_b64 s[0:1], 0
	global_store_dwordx4 v[128:129], v[106:109], off
	global_store_dwordx4 v[128:129], v[150:153], off offset:16

; __device__ __forceinline__ float silu_f(float x) { return x * __builtin_amdgcn_rcpf(1.f + __expf(-x)); }
; __device__ __forceinline__ v4u pack8(const float (&y)[8]) { return (v4u){pk2(y[0], y[1]), pk2(y[2], y[3]), pk2(y[4], y[5]), pk2(y[6], y[7])}; }
;     __device__ __forceinline__ void operator()(const f32x4 (&acc)[2][2][4][2], const pg8::Unit& u, int wr, int wc, int fr, int fq) const {
;     ...
;                         const int row = lrow0 + ai * 128 + m * 16; const size_t off = (size_t)row * 1024 + c;
;                         const f32x4 v0 = acc[ai][bj][m][0] * rs[ai][m], v1 = acc[ai][bj][m][1] * rs[ai][m];
;                         const float v[8] = {v0[0], v0[1], v0[2], v0[3], v1[0], v1[1], v1[2], v1[3]};
;                         float y[8];
;                         if (region == 0) {
; #pragma unroll
;                             for (int j = 0; j < 8; ++j) y[j] = silu_f(v[j]);
;                             *(v4u*)(o0 + off) = pack8(y);
;                         } else if (region == 1) {
;                             float lf[8];
; #pragma unroll
;                             for (int j = 0; j < 8; ++j) {
;                                 const float om = 1.f - lb[j];
;                                 const float fc = fminf(fmaxf(v[j], -80.f), 80.f);
;                                 const float e = __expf(-fc), sg = __builtin_amdgcn_rcpf(1.f + e);
;                                 y[j] = om * e * sg;
;                                 lf[j] = __logf(fmaxf(lb[j] + om * sg, 1e-30f));
;                             }
;                             *(v4u*)(o1 + off) = pack8(y);
;                             *(f32x4*)(of + off) = (f32x4){lf[0], lf[1], lf[2], lf[3]}; *(f32x4*)(of + off + 4) = (f32x4){lf[4], lf[5], lf[6], lf[7]};
.LBB0_951:
	s_nop 1
	v_fmamk_f32 v106, v203, 0x3a800000, v139
	s_mov_b64 s[0:1], -1
	s_nop 0
	v_rsq_f32_e32 v108, v106
	v_or_b32_e32 v106, 48, v178
	v_ashrrev_i32_e32 v107, 31, v106
	v_lshlrev_b64 v[106:107], 10, v[106:107]
	s_nop 0
	v_or_b32_e32 v110, v106, v198
	v_mov_b32_e32 v111, v107
	v_pk_mul_f32 v[112:113], v[104:105], v[108:109] op_sel_hi:[1,0]
	v_pk_mul_f32 v[118:119], v[102:103], v[108:109] op_sel_hi:[1,0]
	v_pk_mul_f32 v[102:103], v[100:101], v[108:109] op_sel_hi:[1,0]
	v_pk_mul_f32 v[104:105], v[98:99], v[108:109] op_sel_hi:[1,0]
	s_and_b64 vcc, exec, s[44:45]
	s_cbranch_vccnz .LBB0_960
	s_and_b64 vcc, exec, s[42:43]
	s_cbranch_vccnz .LBB0_954
	v_max_f32_e32 v98, v118, v118
	s_mov_b32 s39, 0xc2a00000
	v_med3_f32 v98, v98, s39, v195
	v_mul_f32_e32 v98, 0xbfb8aa3b, v98
	v_exp_f32_e32 v98, v98
	v_pk_add_f32 v[126:127], v[176:177], 1.0 op_sel_hi:[1,0] neg_lo:[1,0] neg_hi:[1,0]
	s_mov_b32 s13, 0x3f317217
	s_mov_b32 s15, 0x7f800000
	v_add_f32_e32 v99, 1.0, v98
	v_rcp_f32_e32 v100, v99
	v_max_f32_e32 v99, v119, v119
	v_med3_f32 v99, v99, s39, v195
	v_mul_f32_e32 v99, 0xbfb8aa3b, v99
	v_exp_f32_e32 v99, v99
	v_pk_add_f32 v[150:151], v[174:175], 1.0 op_sel_hi:[1,0] neg_lo:[1,0] neg_hi:[1,0]
	v_pk_add_f32 v[152:153], v[172:173], 1.0 op_sel_hi:[1,0] neg_lo:[1,0] neg_hi:[1,0]
	v_pk_add_f32 v[156:157], v[170:171], 1.0 op_sel_hi:[1,0] neg_lo:[1,0] neg_hi:[1,0]
	v_add_f32_e32 v101, 1.0, v99
	v_rcp_f32_e32 v101, v101
	v_pk_mul_f32 v[98:99], v[98:99], v[126:127]
	s_nop 0
	v_pk_mul_f32 v[120:121], v[100:101], v[98:99]
	v_fma_f32 v98, v100, v126, v176
	v_max_f32_e32 v98, 0xda24260, v98
	s_nop 1
	v_log_f32_e32 v98, v98
	s_nop 0
	v_mul_f32_e32 v99, 0x3f317217, v98
	v_fma_f32 v99, v98, s13, -v99
	v_fmac_f32_e32 v99, 0x3377d1cf, v98
	v_fmac_f32_e32 v99, 0x3f317217, v98
	s_nop 1
	v_mov_b32_e32 v98, v99
	v_fma_f32 v99, v101, v127, v177
	v_max_f32_e32 v99, 0xda24260, v99
	s_nop 1
	v_log_f32_e32 v99, v99
	s_nop 0
	v_mul_f32_e32 v100, 0x3f317217, v99
	v_fma_f32 v100, v99, s13, -v100
	v_fmac_f32_e32 v100, 0x3377d1cf, v99
	v_fmac_f32_e32 v100, 0x3f317217, v99
	s_nop 1
	v_mov_b32_e32 v99, v100
	v_max_f32_e32 v100, v112, v112
	v_med3_f32 v100, v100, s39, v195
	v_mul_f32_e32 v100, 0xbfb8aa3b, v100
	v_exp_f32_e32 v100, v100
	s_nop 0
	v_add_f32_e32 v101, 1.0, v100
	v_rcp_f32_e32 v128, v101
	v_max_f32_e32 v101, v113, v113
	v_med3_f32 v101, v101, s39, v195
	v_mul_f32_e32 v101, 0xbfb8aa3b, v101
	v_exp_f32_e32 v101, v101
	s_nop 0
	v_add_f32_e32 v109, 1.0, v101
	v_rcp_f32_e32 v129, v109
	v_pk_mul_f32 v[100:101], v[100:101], v[150:151]
	s_nop 0
	v_pk_mul_f32 v[126:127], v[128:129], v[100:101]
	v_fma_f32 v100, v128, v150, v174
	v_max_f32_e32 v100, 0xda24260, v100
	s_nop 1
	v_log_f32_e32 v100, v100
	s_nop 0
	v_mul_f32_e32 v101, 0x3f317217, v100
	v_fma_f32 v101, v100, s13, -v101
	v_fmac_f32_e32 v101, 0x3377d1cf, v100
	v_fmac_f32_e32 v101, 0x3f317217, v100
	s_nop 1
	v_mov_b32_e32 v100, v101
	v_fma_f32 v101, v129, v151, v175
	v_max_f32_e32 v101, 0xda24260, v101
	s_nop 1
	v_log_f32_e32 v101, v101
	s_nop 0
	v_mul_f32_e32 v109, 0x3f317217, v101
	v_fma_f32 v109, v101, s13, -v109
	v_fmac_f32_e32 v109, 0x3377d1cf, v101
	v_fmac_f32_e32 v109, 0x3f317217, v101
	s_nop 1
	v_mov_b32_e32 v101, v109
	v_max_f32_e32 v109, v104, v104
	v_med3_f32 v109, v109, s39, v195
	v_mul_f32_e32 v109, 0xbfb8aa3b, v109
	v_exp_f32_e32 v128, v109
	s_nop 0
	v_add_f32_e32 v109, 1.0, v128
	v_rcp_f32_e32 v150, v109
	v_max_f32_e32 v109, v105, v105
	v_med3_f32 v109, v109, s39, v195
	v_mul_f32_e32 v109, 0xbfb8aa3b, v109
	v_exp_f32_e32 v129, v109
	s_nop 0
	v_add_f32_e32 v109, 1.0, v129
	v_rcp_f32_e32 v151, v109
	v_fma_f32 v109, v150, v152, v172
	v_max_f32_e32 v109, 0xda24260, v109
	v_pk_mul_f32 v[128:129], v[128:129], v[152:153]
	s_nop 0
	v_log_f32_e32 v109, v109
	v_pk_mul_f32 v[128:129], v[150:151], v[128:129]
	v_mul_f32_e32 v117, 0x3f317217, v109
	v_fma_f32 v117, v109, s13, -v117
	v_fmac_f32_e32 v117, 0x3377d1cf, v109
	v_fmac_f32_e32 v117, 0x3f317217, v109
	s_nop 1
	v_mov_b32_e32 v109, v117
	v_mov_b32_e32 v150, v109
	v_fma_f32 v109, v151, v153, v173
	v_max_f32_e32 v109, 0xda24260, v109
	s_nop 1
	v_log_f32_e32 v109, v109
	s_nop 0
	v_mul_f32_e32 v117, 0x3f317217, v109
	v_fma_f32 v117, v109, s13, -v117
	v_fmac_f32_e32 v117, 0x3377d1cf, v109
	v_fmac_f32_e32 v117, 0x3f317217, v109
	s_nop 1
	v_mov_b32_e32 v109, v117
	v_mov_b32_e32 v151, v109
	v_max_f32_e32 v109, v102, v102
	v_med3_f32 v109, v109, s39, v195
	v_mul_f32_e32 v109, 0xbfb8aa3b, v109
	v_exp_f32_e32 v152, v109
	s_nop 0
	v_add_f32_e32 v109, 1.0, v152
	v_rcp_f32_e32 v154, v109
	v_max_f32_e32 v109, v103, v103
	v_med3_f32 v109, v109, s39, v195
	v_mul_f32_e32 v109, 0xbfb8aa3b, v109
	v_exp_f32_e32 v153, v109
	s_nop 0
	v_add_f32_e32 v109, 1.0, v153
	v_rcp_f32_e32 v155, v109
	v_fma_f32 v109, v154, v156, v170
	v_max_f32_e32 v109, 0xda24260, v109
	v_pk_mul_f32 v[152:153], v[152:153], v[156:157]
	v_cvt_pk_bf16_f32 v156, v128, v129
	v_log_f32_e32 v109, v109
	v_pk_mul_f32 v[158:159], v[154:155], v[152:153]
	v_cvt_pk_bf16_f32 v154, v120, v121
	v_mul_f32_e32 v117, 0x3f317217, v109
	v_fma_f32 v117, v109, s13, -v117
	v_fmac_f32_e32 v117, 0x3377d1cf, v109
	v_fmac_f32_e32 v117, 0x3f317217, v109
	s_nop 1
	v_mov_b32_e32 v109, v117
	v_mov_b32_e32 v152, v109
	v_fma_f32 v109, v155, v157, v171
	v_max_f32_e32 v109, 0xda24260, v109
	v_cvt_pk_bf16_f32 v155, v126, v127
	v_cvt_pk_bf16_f32 v157, v158, v159
	v_log_f32_e32 v109, v109
	s_nop 0
	v_mul_f32_e32 v117, 0x3f317217, v109
	v_fma_f32 v117, v109, s13, -v117
	v_fmac_f32_e32 v117, 0x3377d1cf, v109
	v_fmac_f32_e32 v117, 0x3f317217, v109
	s_nop 1
	v_mov_b32_e32 v109, v117
	v_readlane_b32 s0, v253, 0
	v_readlane_b32 s1, v253, 1
	v_mov_b32_e32 v153, v109
	v_lshl_add_u64 v[120:121], v[110:111], 1, s[0:1]
	global_store_dwordx4 v[120:121], v[154:157], off
	v_lshl_add_u64 v[120:121], v[110:111], 2, s[2:3]
	s_mov_b64 s[0:1], 0
	global_store_dwordx4 v[120:121], v[98:101], off
	global_store_dwordx4 v[120:121], v[150:153], off offset:16

; __device__ __forceinline__ float silu_f(float x) { return x * __builtin_amdgcn_rcpf(1.f + __expf(-x)); }
; __device__ __forceinline__ v4u pack8(const float (&y)[8]) { return (v4u){pk2(y[0], y[1]), pk2(y[2], y[3]), pk2(y[4], y[5]), pk2(y[6], y[7])}; }
;     __device__ __forceinline__ void operator()(const f32x4 (&acc)[2][2][4][2], const pg8::Unit& u, int wr, int wc, int fr, int fq) const {
;     ...
;                         const int row = lrow0 + ai * 128 + m * 16; const size_t off = (size_t)row * 1024 + c;
;                         const f32x4 v0 = acc[ai][bj][m][0] * rs[ai][m], v1 = acc[ai][bj][m][1] * rs[ai][m];
;                         const float v[8] = {v0[0], v0[1], v0[2], v0[3], v1[0], v1[1], v1[2], v1[3]};
;                         float y[8];
;                         if (region == 0) {
; #pragma unroll
;                             for (int j = 0; j < 8; ++j) y[j] = silu_f(v[j]);
;                             *(v4u*)(o0 + off) = pack8(y);
;                         } else if (region == 1) {
;                             float lf[8];
; #pragma unroll
;                             for (int j = 0; j < 8; ++j) {
;                                 const float om = 1.f - lb[j];
;                                 const float fc = fminf(fmaxf(v[j], -80.f), 80.f);
;                                 const float e = __expf(-fc), sg = __builtin_amdgcn_rcpf(1.f + e);
;                                 y[j] = om * e * sg;
;                                 lf[j] = __logf(fmaxf(lb[j] + om * sg, 1e-30f));
;                             }
;                             *(v4u*)(o1 + off) = pack8(y);
;                             *(f32x4*)(of + off) = (f32x4){lf[0], lf[1], lf[2], lf[3]}; *(f32x4*)(of + off + 4) = (f32x4){lf[4], lf[5], lf[6], lf[7]};
.LBB0_962:
	s_nop 1
	v_fmamk_f32 v98, v202, 0x3a800000, v139
	s_mov_b64 s[0:1], 0x20000
	s_nop 0
	v_rsq_f32_e32 v100, v98
	v_lshlrev_b64 v[98:99], 10, v[178:179]
	v_lshl_add_u64 v[98:99], v[98:99], 0, s[0:1]
	v_or_b32_e32 v102, v98, v198
	s_nop 0
	v_mov_b32_e32 v103, v99
	v_pk_mul_f32 v[104:105], v[96:97], v[100:101] op_sel_hi:[1,0]
	v_pk_mul_f32 v[110:111], v[94:95], v[100:101] op_sel_hi:[1,0]
	v_pk_mul_f32 v[94:95], v[92:93], v[100:101] op_sel_hi:[1,0]
	v_pk_mul_f32 v[96:97], v[90:91], v[100:101] op_sel_hi:[1,0]
	s_and_b64 vcc, exec, s[44:45]
	s_mov_b64 s[0:1], -1
	s_cbranch_vccnz .LBB0_971
	s_and_b64 vcc, exec, s[42:43]
	s_cbranch_vccnz .LBB0_965
	v_max_f32_e32 v90, v110, v110
	s_mov_b32 s39, 0xc2a00000
	v_med3_f32 v90, v90, s39, v195
	v_mul_f32_e32 v90, 0xbfb8aa3b, v90
	v_exp_f32_e32 v90, v90
	v_pk_add_f32 v[118:119], v[176:177], 1.0 op_sel_hi:[1,0] neg_lo:[1,0] neg_hi:[1,0]
	s_mov_b32 s13, 0x3f317217
	s_mov_b32 s15, 0x7f800000
	v_add_f32_e32 v91, 1.0, v90
	v_rcp_f32_e32 v92, v91
	v_max_f32_e32 v91, v111, v111
	v_med3_f32 v91, v91, s39, v195
	v_mul_f32_e32 v91, 0xbfb8aa3b, v91
	v_exp_f32_e32 v91, v91
	v_pk_add_f32 v[126:127], v[174:175], 1.0 op_sel_hi:[1,0] neg_lo:[1,0] neg_hi:[1,0]
	v_pk_add_f32 v[128:129], v[172:173], 1.0 op_sel_hi:[1,0] neg_lo:[1,0] neg_hi:[1,0]
	v_pk_add_f32 v[152:153], v[170:171], 1.0 op_sel_hi:[1,0] neg_lo:[1,0] neg_hi:[1,0]
	v_add_f32_e32 v93, 1.0, v91
	v_rcp_f32_e32 v93, v93
	v_pk_mul_f32 v[90:91], v[90:91], v[118:119]
	s_nop 0
	v_pk_mul_f32 v[112:113], v[92:93], v[90:91]
	v_fma_f32 v90, v92, v118, v176
	v_max_f32_e32 v90, 0xda24260, v90
	s_nop 1
	v_log_f32_e32 v90, v90
	s_nop 0
	v_mul_f32_e32 v91, 0x3f317217, v90
	v_fma_f32 v91, v90, s13, -v91
	v_fmac_f32_e32 v91, 0x3377d1cf, v90
	v_fmac_f32_e32 v91, 0x3f317217, v90
	s_nop 1
	v_mov_b32_e32 v90, v91
	v_fma_f32 v91, v93, v119, v177
	v_max_f32_e32 v91, 0xda24260, v91
	s_nop 1
	v_log_f32_e32 v91, v91
	s_nop 0
	v_mul_f32_e32 v92, 0x3f317217, v91
	v_fma_f32 v92, v91, s13, -v92
	v_fmac_f32_e32 v92, 0x3377d1cf, v91
	v_fmac_f32_e32 v92, 0x3f317217, v91
	s_nop 1
	v_mov_b32_e32 v91, v92
	v_max_f32_e32 v92, v104, v104
	v_med3_f32 v92, v92, s39, v195
	v_mul_f32_e32 v92, 0xbfb8aa3b, v92
	v_exp_f32_e32 v92, v92
	s_nop 0
	v_add_f32_e32 v93, 1.0, v92
	v_rcp_f32_e32 v120, v93
	v_max_f32_e32 v93, v105, v105
	v_med3_f32 v93, v93, s39, v195
	v_mul_f32_e32 v93, 0xbfb8aa3b, v93
	v_exp_f32_e32 v93, v93
	s_nop 0
	v_add_f32_e32 v101, 1.0, v93
	v_rcp_f32_e32 v121, v101
	v_pk_mul_f32 v[92:93], v[92:93], v[126:127]
	s_nop 0
	v_pk_mul_f32 v[118:119], v[120:121], v[92:93]
	v_fma_f32 v92, v120, v126, v174
	v_max_f32_e32 v92, 0xda24260, v92
	s_nop 1
	v_log_f32_e32 v92, v92
	s_nop 0
	v_mul_f32_e32 v93, 0x3f317217, v92
	v_fma_f32 v93, v92, s13, -v93
	v_fmac_f32_e32 v93, 0x3377d1cf, v92
	v_fmac_f32_e32 v93, 0x3f317217, v92
	s_nop 1
	v_mov_b32_e32 v92, v93
	v_fma_f32 v93, v121, v127, v175
	v_max_f32_e32 v93, 0xda24260, v93
	s_nop 1
	v_log_f32_e32 v93, v93
	s_nop 0
	v_mul_f32_e32 v101, 0x3f317217, v93
	v_fma_f32 v101, v93, s13, -v101
	v_fmac_f32_e32 v101, 0x3377d1cf, v93
	v_fmac_f32_e32 v101, 0x3f317217, v93
	s_nop 1
	v_mov_b32_e32 v93, v101
	v_max_f32_e32 v101, v96, v96
	v_med3_f32 v101, v101, s39, v195
	v_mul_f32_e32 v101, 0xbfb8aa3b, v101
	v_exp_f32_e32 v120, v101
	s_nop 0
	v_add_f32_e32 v101, 1.0, v120
	v_rcp_f32_e32 v126, v101
	v_max_f32_e32 v101, v97, v97
	v_med3_f32 v101, v101, s39, v195
	v_mul_f32_e32 v101, 0xbfb8aa3b, v101
	v_exp_f32_e32 v121, v101
	s_nop 0
	v_add_f32_e32 v101, 1.0, v121
	v_rcp_f32_e32 v127, v101
	v_fma_f32 v101, v126, v128, v172
	v_max_f32_e32 v101, 0xda24260, v101
	v_pk_mul_f32 v[120:121], v[120:121], v[128:129]
	s_nop 0
	v_log_f32_e32 v101, v101
	v_pk_mul_f32 v[120:121], v[126:127], v[120:121]
	v_mul_f32_e32 v109, 0x3f317217, v101
	v_fma_f32 v109, v101, s13, -v109
	v_fmac_f32_e32 v109, 0x3377d1cf, v101
	v_fmac_f32_e32 v109, 0x3f317217, v101
	s_nop 1
	v_mov_b32_e32 v101, v109
	v_mov_b32_e32 v126, v101
	v_fma_f32 v101, v127, v129, v173
	v_max_f32_e32 v101, 0xda24260, v101
	s_nop 1
	v_log_f32_e32 v101, v101
	s_nop 0
	v_mul_f32_e32 v109, 0x3f317217, v101
	v_fma_f32 v109, v101, s13, -v109
	v_fmac_f32_e32 v109, 0x3377d1cf, v101
	v_fmac_f32_e32 v109, 0x3f317217, v101
	s_nop 1
	v_mov_b32_e32 v101, v109
	v_mov_b32_e32 v127, v101
	v_max_f32_e32 v101, v94, v94
	v_med3_f32 v101, v101, s39, v195
	v_mul_f32_e32 v101, 0xbfb8aa3b, v101
	v_exp_f32_e32 v128, v101
	s_nop 0
	v_add_f32_e32 v101, 1.0, v128
	v_rcp_f32_e32 v150, v101
	v_max_f32_e32 v101, v95, v95
	v_med3_f32 v101, v101, s39, v195
	v_mul_f32_e32 v101, 0xbfb8aa3b, v101
	v_exp_f32_e32 v129, v101
	s_nop 0
	v_add_f32_e32 v101, 1.0, v129
	v_rcp_f32_e32 v151, v101
	v_fma_f32 v101, v150, v152, v170
	v_max_f32_e32 v101, 0xda24260, v101
	v_pk_mul_f32 v[128:129], v[128:129], v[152:153]
	v_cvt_pk_bf16_f32 v152, v120, v121
	v_log_f32_e32 v101, v101
	v_pk_mul_f32 v[154:155], v[150:151], v[128:129]
	v_cvt_pk_bf16_f32 v150, v112, v113
	v_mul_f32_e32 v109, 0x3f317217, v101
	v_fma_f32 v109, v101, s13, -v109
	v_fmac_f32_e32 v109, 0x3377d1cf, v101
	v_fmac_f32_e32 v109, 0x3f317217, v101
	s_nop 1
	v_mov_b32_e32 v101, v109
	v_mov_b32_e32 v128, v101
	v_fma_f32 v101, v151, v153, v171
	v_max_f32_e32 v101, 0xda24260, v101
	v_cvt_pk_bf16_f32 v151, v118, v119
	v_cvt_pk_bf16_f32 v153, v154, v155
	v_log_f32_e32 v101, v101
	s_nop 0
	v_mul_f32_e32 v109, 0x3f317217, v101
	v_fma_f32 v109, v101, s13, -v109
	v_fmac_f32_e32 v109, 0x3377d1cf, v101
	v_fmac_f32_e32 v109, 0x3f317217, v101
	s_nop 1
	v_mov_b32_e32 v101, v109
	v_readlane_b32 s0, v253, 0
	v_readlane_b32 s1, v253, 1
	v_mov_b32_e32 v129, v101
	v_lshl_add_u64 v[112:113], v[102:103], 1, s[0:1]
	global_store_dwordx4 v[112:113], v[150:153], off
	v_lshl_add_u64 v[112:113], v[102:103], 2, s[2:3]
	s_mov_b64 s[0:1], 0
	global_store_dwordx4 v[112:113], v[90:93], off
	global_store_dwordx4 v[112:113], v[126:129], off offset:16

; __device__ __forceinline__ float silu_f(float x) { return x * __builtin_amdgcn_rcpf(1.f + __expf(-x)); }
; __device__ __forceinline__ v4u pack8(const float (&y)[8]) { return (v4u){pk2(y[0], y[1]), pk2(y[2], y[3]), pk2(y[4], y[5]), pk2(y[6], y[7])}; }
;     __device__ __forceinline__ void operator()(const f32x4 (&acc)[2][2][4][2], const pg8::Unit& u, int wr, int wc, int fr, int fq) const {
;     ...
;                         const int row = lrow0 + ai * 128 + m * 16; const size_t off = (size_t)row * 1024 + c;
;                         const f32x4 v0 = acc[ai][bj][m][0] * rs[ai][m], v1 = acc[ai][bj][m][1] * rs[ai][m];
;                         const float v[8] = {v0[0], v0[1], v0[2], v0[3], v1[0], v1[1], v1[2], v1[3]};
;                         float y[8];
;                         if (region == 0) {
; #pragma unroll
;                             for (int j = 0; j < 8; ++j) y[j] = silu_f(v[j]);
;                             *(v4u*)(o0 + off) = pack8(y);
;                         } else if (region == 1) {
;                             float lf[8];
; #pragma unroll
;                             for (int j = 0; j < 8; ++j) {
;                                 const float om = 1.f - lb[j];
;                                 const float fc = fminf(fmaxf(v[j], -80.f), 80.f);
;                                 const float e = __expf(-fc), sg = __builtin_amdgcn_rcpf(1.f + e);
;                                 y[j] = om * e * sg;
;                                 lf[j] = __logf(fmaxf(lb[j] + om * sg, 1e-30f));
;                             }
;                             *(v4u*)(o1 + off) = pack8(y);
;                             *(f32x4*)(of + off) = (f32x4){lf[0], lf[1], lf[2], lf[3]}; *(f32x4*)(of + off + 4) = (f32x4){lf[4], lf[5], lf[6], lf[7]};
.LBB0_973:
	s_nop 1
	v_fmamk_f32 v90, v201, 0x3a800000, v139
	s_mov_b64 s[0:1], 0x24000
	s_nop 0
	v_rsq_f32_e32 v92, v90
	v_lshlrev_b64 v[90:91], 10, v[178:179]
	v_lshl_add_u64 v[90:91], v[90:91], 0, s[0:1]
	v_or_b32_e32 v94, v90, v198
	s_nop 0
	v_mov_b32_e32 v95, v91
	v_pk_mul_f32 v[96:97], v[88:89], v[92:93] op_sel_hi:[1,0]
	v_pk_mul_f32 v[102:103], v[86:87], v[92:93] op_sel_hi:[1,0]
	v_pk_mul_f32 v[86:87], v[84:85], v[92:93] op_sel_hi:[1,0]
	v_pk_mul_f32 v[88:89], v[82:83], v[92:93] op_sel_hi:[1,0]
	s_and_b64 vcc, exec, s[44:45]
	s_mov_b64 s[0:1], -1
	s_cbranch_vccnz .LBB0_982
	s_and_b64 vcc, exec, s[42:43]
	s_cbranch_vccnz .LBB0_976
	v_max_f32_e32 v82, v102, v102
	s_mov_b32 s39, 0xc2a00000
	v_med3_f32 v82, v82, s39, v195
	v_mul_f32_e32 v82, 0xbfb8aa3b, v82
	v_exp_f32_e32 v82, v82
	v_pk_add_f32 v[110:111], v[176:177], 1.0 op_sel_hi:[1,0] neg_lo:[1,0] neg_hi:[1,0]
	s_mov_b32 s13, 0x3f317217
	s_mov_b32 s15, 0x7f800000
	v_add_f32_e32 v83, 1.0, v82
	v_rcp_f32_e32 v84, v83
	v_max_f32_e32 v83, v103, v103
	v_med3_f32 v83, v83, s39, v195
	v_mul_f32_e32 v83, 0xbfb8aa3b, v83
	v_exp_f32_e32 v83, v83
	v_pk_add_f32 v[118:119], v[174:175], 1.0 op_sel_hi:[1,0] neg_lo:[1,0] neg_hi:[1,0]
	v_pk_add_f32 v[120:121], v[172:173], 1.0 op_sel_hi:[1,0] neg_lo:[1,0] neg_hi:[1,0]
	v_pk_add_f32 v[128:129], v[170:171], 1.0 op_sel_hi:[1,0] neg_lo:[1,0] neg_hi:[1,0]
	v_add_f32_e32 v85, 1.0, v83
	v_rcp_f32_e32 v85, v85
	v_pk_mul_f32 v[82:83], v[82:83], v[110:111]
	s_nop 0
	v_pk_mul_f32 v[104:105], v[84:85], v[82:83]
	v_fma_f32 v82, v84, v110, v176
	v_max_f32_e32 v82, 0xda24260, v82
	s_nop 1
	v_log_f32_e32 v82, v82
	s_nop 0
	v_mul_f32_e32 v83, 0x3f317217, v82
	v_fma_f32 v83, v82, s13, -v83
	v_fmac_f32_e32 v83, 0x3377d1cf, v82
	v_fmac_f32_e32 v83, 0x3f317217, v82
	s_nop 1
	v_mov_b32_e32 v82, v83
	v_fma_f32 v83, v85, v111, v177
	v_max_f32_e32 v83, 0xda24260, v83
	s_nop 1
	v_log_f32_e32 v83, v83
	s_nop 0
	v_mul_f32_e32 v84, 0x3f317217, v83
	v_fma_f32 v84, v83, s13, -v84
	v_fmac_f32_e32 v84, 0x3377d1cf, v83
	v_fmac_f32_e32 v84, 0x3f317217, v83
	s_nop 1
	v_mov_b32_e32 v83, v84
	v_max_f32_e32 v84, v96, v96
	v_med3_f32 v84, v84, s39, v195
	v_mul_f32_e32 v84, 0xbfb8aa3b, v84
	v_exp_f32_e32 v84, v84
	s_nop 0
	v_add_f32_e32 v85, 1.0, v84
	v_rcp_f32_e32 v112, v85
	v_max_f32_e32 v85, v97, v97
	v_med3_f32 v85, v85, s39, v195
	v_mul_f32_e32 v85, 0xbfb8aa3b, v85
	v_exp_f32_e32 v85, v85
	s_nop 0
	v_add_f32_e32 v93, 1.0, v85
	v_rcp_f32_e32 v113, v93
	v_pk_mul_f32 v[84:85], v[84:85], v[118:119]
	s_nop 0
	v_pk_mul_f32 v[110:111], v[112:113], v[84:85]
	v_fma_f32 v84, v112, v118, v174
	v_max_f32_e32 v84, 0xda24260, v84
	s_nop 1
	v_log_f32_e32 v84, v84
	s_nop 0
	v_mul_f32_e32 v85, 0x3f317217, v84
	v_fma_f32 v85, v84, s13, -v85
	v_fmac_f32_e32 v85, 0x3377d1cf, v84
	v_fmac_f32_e32 v85, 0x3f317217, v84
	s_nop 1
	v_mov_b32_e32 v84, v85
	v_fma_f32 v85, v113, v119, v175
	v_max_f32_e32 v85, 0xda24260, v85
	s_nop 1
	v_log_f32_e32 v85, v85
	s_nop 0
	v_mul_f32_e32 v93, 0x3f317217, v85
	v_fma_f32 v93, v85, s13, -v93
	v_fmac_f32_e32 v93, 0x3377d1cf, v85
	v_fmac_f32_e32 v93, 0x3f317217, v85
	s_nop 1
	v_mov_b32_e32 v85, v93
	v_max_f32_e32 v93, v88, v88
	v_med3_f32 v93, v93, s39, v195
	v_mul_f32_e32 v93, 0xbfb8aa3b, v93
	v_exp_f32_e32 v112, v93
	s_nop 0
	v_add_f32_e32 v93, 1.0, v112
	v_rcp_f32_e32 v118, v93
	v_max_f32_e32 v93, v89, v89
	v_med3_f32 v93, v93, s39, v195
	v_mul_f32_e32 v93, 0xbfb8aa3b, v93
	v_exp_f32_e32 v113, v93
	s_nop 0
	v_add_f32_e32 v93, 1.0, v113
	v_rcp_f32_e32 v119, v93
	v_fma_f32 v93, v118, v120, v172
	v_max_f32_e32 v93, 0xda24260, v93
	v_pk_mul_f32 v[112:113], v[112:113], v[120:121]
	s_nop 0
	v_log_f32_e32 v93, v93
	v_pk_mul_f32 v[112:113], v[118:119], v[112:113]
	v_mul_f32_e32 v101, 0x3f317217, v93
	v_fma_f32 v101, v93, s13, -v101
	v_fmac_f32_e32 v101, 0x3377d1cf, v93
	v_fmac_f32_e32 v101, 0x3f317217, v93
	s_nop 1
	v_mov_b32_e32 v93, v101
	v_mov_b32_e32 v118, v93
	v_fma_f32 v93, v119, v121, v173
	v_max_f32_e32 v93, 0xda24260, v93
	s_nop 1
	v_log_f32_e32 v93, v93
	s_nop 0
	v_mul_f32_e32 v101, 0x3f317217, v93
	v_fma_f32 v101, v93, s13, -v101
	v_fmac_f32_e32 v101, 0x3377d1cf, v93
	v_fmac_f32_e32 v101, 0x3f317217, v93
	s_nop 1
	v_mov_b32_e32 v93, v101
	v_mov_b32_e32 v119, v93
	v_max_f32_e32 v93, v86, v86
	v_med3_f32 v93, v93, s39, v195
	v_mul_f32_e32 v93, 0xbfb8aa3b, v93
	v_exp_f32_e32 v120, v93
	s_nop 0
	v_add_f32_e32 v93, 1.0, v120
	v_rcp_f32_e32 v126, v93
	v_max_f32_e32 v93, v87, v87
	v_med3_f32 v93, v93, s39, v195
	v_mul_f32_e32 v93, 0xbfb8aa3b, v93
	v_exp_f32_e32 v121, v93
	s_nop 0
	v_add_f32_e32 v93, 1.0, v121
	v_rcp_f32_e32 v127, v93
	v_fma_f32 v93, v126, v128, v170
	v_max_f32_e32 v93, 0xda24260, v93
	v_pk_mul_f32 v[120:121], v[120:121], v[128:129]
	v_cvt_pk_bf16_f32 v128, v112, v113
	v_log_f32_e32 v93, v93
	v_pk_mul_f32 v[150:151], v[126:127], v[120:121]
	v_cvt_pk_bf16_f32 v126, v104, v105
	v_mul_f32_e32 v101, 0x3f317217, v93
	v_fma_f32 v101, v93, s13, -v101
	v_fmac_f32_e32 v101, 0x3377d1cf, v93
	v_fmac_f32_e32 v101, 0x3f317217, v93
	s_nop 1
	v_mov_b32_e32 v93, v101
	v_mov_b32_e32 v120, v93
	v_fma_f32 v93, v127, v129, v171
	v_max_f32_e32 v93, 0xda24260, v93
	v_cvt_pk_bf16_f32 v127, v110, v111
	v_cvt_pk_bf16_f32 v129, v150, v151
	v_log_f32_e32 v93, v93
	s_nop 0
	v_mul_f32_e32 v101, 0x3f317217, v93
	v_fma_f32 v101, v93, s13, -v101
	v_fmac_f32_e32 v101, 0x3377d1cf, v93
	v_fmac_f32_e32 v101, 0x3f317217, v93
	s_nop 1
	v_mov_b32_e32 v93, v101
	v_readlane_b32 s0, v253, 0
	v_readlane_b32 s1, v253, 1
	v_mov_b32_e32 v121, v93
	v_lshl_add_u64 v[104:105], v[94:95], 1, s[0:1]
	global_store_dwordx4 v[104:105], v[126:129], off
	v_lshl_add_u64 v[104:105], v[94:95], 2, s[2:3]
	s_mov_b64 s[0:1], 0
	global_store_dwordx4 v[104:105], v[82:85], off
	global_store_dwordx4 v[104:105], v[118:121], off offset:16

; __device__ __forceinline__ float silu_f(float x) { return x * __builtin_amdgcn_rcpf(1.f + __expf(-x)); }
; __device__ __forceinline__ v4u pack8(const float (&y)[8]) { return (v4u){pk2(y[0], y[1]), pk2(y[2], y[3]), pk2(y[4], y[5]), pk2(y[6], y[7])}; }
;     __device__ __forceinline__ void operator()(const f32x4 (&acc)[2][2][4][2], const pg8::Unit& u, int wr, int wc, int fr, int fq) const {
;     ...
;                         const int row = lrow0 + ai * 128 + m * 16; const size_t off = (size_t)row * 1024 + c;
;                         const f32x4 v0 = acc[ai][bj][m][0] * rs[ai][m], v1 = acc[ai][bj][m][1] * rs[ai][m];
;                         const float v[8] = {v0[0], v0[1], v0[2], v0[3], v1[0], v1[1], v1[2], v1[3]};
;                         float y[8];
;                         if (region == 0) {
; #pragma unroll
;                             for (int j = 0; j < 8; ++j) y[j] = silu_f(v[j]);
;                             *(v4u*)(o0 + off) = pack8(y);
;                         } else if (region == 1) {
;                             float lf[8];
; #pragma unroll
;                             for (int j = 0; j < 8; ++j) {
;                                 const float om = 1.f - lb[j];
;                                 const float fc = fminf(fmaxf(v[j], -80.f), 80.f);
;                                 const float e = __expf(-fc), sg = __builtin_amdgcn_rcpf(1.f + e);
;                                 y[j] = om * e * sg;
;                                 lf[j] = __logf(fmaxf(lb[j] + om * sg, 1e-30f));
;                             }
;                             *(v4u*)(o1 + off) = pack8(y);
;                             *(f32x4*)(of + off) = (f32x4){lf[0], lf[1], lf[2], lf[3]}; *(f32x4*)(of + off + 4) = (f32x4){lf[4], lf[5], lf[6], lf[7]};
.LBB0_984:
	s_nop 1
	v_fmamk_f32 v82, v200, 0x3a800000, v139
	s_mov_b64 s[0:1], 0x28000
	s_nop 0
	v_rsq_f32_e32 v84, v82
	v_lshlrev_b64 v[82:83], 10, v[178:179]
	v_lshl_add_u64 v[82:83], v[82:83], 0, s[0:1]
	v_or_b32_e32 v86, v82, v198
	s_nop 0
	v_mov_b32_e32 v87, v83
	v_pk_mul_f32 v[88:89], v[80:81], v[84:85] op_sel_hi:[1,0]
	v_pk_mul_f32 v[94:95], v[78:79], v[84:85] op_sel_hi:[1,0]
	v_pk_mul_f32 v[78:79], v[76:77], v[84:85] op_sel_hi:[1,0]
	v_pk_mul_f32 v[80:81], v[74:75], v[84:85] op_sel_hi:[1,0]
	s_and_b64 vcc, exec, s[44:45]
	s_mov_b64 s[0:1], -1
	s_cbranch_vccnz .LBB0_993
	s_and_b64 vcc, exec, s[42:43]
	s_cbranch_vccnz .LBB0_987
	v_max_f32_e32 v74, v94, v94
	s_mov_b32 s39, 0xc2a00000
	v_med3_f32 v74, v74, s39, v195
	v_mul_f32_e32 v74, 0xbfb8aa3b, v74
	v_exp_f32_e32 v74, v74
	v_pk_add_f32 v[102:103], v[176:177], 1.0 op_sel_hi:[1,0] neg_lo:[1,0] neg_hi:[1,0]
	s_mov_b32 s13, 0x3f317217
	s_mov_b32 s15, 0x7f800000
	v_add_f32_e32 v75, 1.0, v74
	v_rcp_f32_e32 v76, v75
	v_max_f32_e32 v75, v95, v95
	v_med3_f32 v75, v75, s39, v195
	v_mul_f32_e32 v75, 0xbfb8aa3b, v75
	v_exp_f32_e32 v75, v75
	v_pk_add_f32 v[110:111], v[174:175], 1.0 op_sel_hi:[1,0] neg_lo:[1,0] neg_hi:[1,0]
	v_pk_add_f32 v[112:113], v[172:173], 1.0 op_sel_hi:[1,0] neg_lo:[1,0] neg_hi:[1,0]
	v_pk_add_f32 v[120:121], v[170:171], 1.0 op_sel_hi:[1,0] neg_lo:[1,0] neg_hi:[1,0]
	v_add_f32_e32 v77, 1.0, v75
	v_rcp_f32_e32 v77, v77
	v_pk_mul_f32 v[74:75], v[74:75], v[102:103]
	s_nop 0
	v_pk_mul_f32 v[96:97], v[76:77], v[74:75]
	v_fma_f32 v74, v76, v102, v176
	v_max_f32_e32 v74, 0xda24260, v74
	s_nop 1
	v_log_f32_e32 v74, v74
	s_nop 0
	v_mul_f32_e32 v75, 0x3f317217, v74
	v_fma_f32 v75, v74, s13, -v75
	v_fmac_f32_e32 v75, 0x3377d1cf, v74
	v_fmac_f32_e32 v75, 0x3f317217, v74
	s_nop 1
	v_mov_b32_e32 v74, v75
	v_fma_f32 v75, v77, v103, v177
	v_max_f32_e32 v75, 0xda24260, v75
	s_nop 1
	v_log_f32_e32 v75, v75
	s_nop 0
	v_mul_f32_e32 v76, 0x3f317217, v75
	v_fma_f32 v76, v75, s13, -v76
	v_fmac_f32_e32 v76, 0x3377d1cf, v75
	v_fmac_f32_e32 v76, 0x3f317217, v75
	s_nop 1
	v_mov_b32_e32 v75, v76
	v_max_f32_e32 v76, v88, v88
	v_med3_f32 v76, v76, s39, v195
	v_mul_f32_e32 v76, 0xbfb8aa3b, v76
	v_exp_f32_e32 v76, v76
	s_nop 0
	v_add_f32_e32 v77, 1.0, v76
	v_rcp_f32_e32 v104, v77
	v_max_f32_e32 v77, v89, v89
	v_med3_f32 v77, v77, s39, v195
	v_mul_f32_e32 v77, 0xbfb8aa3b, v77
	v_exp_f32_e32 v77, v77
	s_nop 0
	v_add_f32_e32 v85, 1.0, v77
	v_rcp_f32_e32 v105, v85
	v_pk_mul_f32 v[76:77], v[76:77], v[110:111]
	s_nop 0
	v_pk_mul_f32 v[102:103], v[104:105], v[76:77]
	v_fma_f32 v76, v104, v110, v174
	v_max_f32_e32 v76, 0xda24260, v76
	s_nop 1
	v_log_f32_e32 v76, v76
	s_nop 0
	v_mul_f32_e32 v77, 0x3f317217, v76
	v_fma_f32 v77, v76, s13, -v77
	v_fmac_f32_e32 v77, 0x3377d1cf, v76
	v_fmac_f32_e32 v77, 0x3f317217, v76
	s_nop 1
	v_mov_b32_e32 v76, v77
	v_fma_f32 v77, v105, v111, v175
	v_max_f32_e32 v77, 0xda24260, v77
	s_nop 1
	v_log_f32_e32 v77, v77
	s_nop 0
	v_mul_f32_e32 v85, 0x3f317217, v77
	v_fma_f32 v85, v77, s13, -v85
	v_fmac_f32_e32 v85, 0x3377d1cf, v77
	v_fmac_f32_e32 v85, 0x3f317217, v77
	s_nop 1
	v_mov_b32_e32 v77, v85
	v_max_f32_e32 v85, v80, v80
	v_med3_f32 v85, v85, s39, v195
	v_mul_f32_e32 v85, 0xbfb8aa3b, v85
	v_exp_f32_e32 v104, v85
	s_nop 0
	v_add_f32_e32 v85, 1.0, v104
	v_rcp_f32_e32 v110, v85
	v_max_f32_e32 v85, v81, v81
	v_med3_f32 v85, v85, s39, v195
	v_mul_f32_e32 v85, 0xbfb8aa3b, v85
	v_exp_f32_e32 v105, v85
	s_nop 0
	v_add_f32_e32 v85, 1.0, v105
	v_rcp_f32_e32 v111, v85
	v_fma_f32 v85, v110, v112, v172
	v_max_f32_e32 v85, 0xda24260, v85
	v_pk_mul_f32 v[104:105], v[104:105], v[112:113]
	s_nop 0
	v_log_f32_e32 v85, v85
	v_pk_mul_f32 v[104:105], v[110:111], v[104:105]
	v_mul_f32_e32 v93, 0x3f317217, v85
	v_fma_f32 v93, v85, s13, -v93
	v_fmac_f32_e32 v93, 0x3377d1cf, v85
	v_fmac_f32_e32 v93, 0x3f317217, v85
	s_nop 1
	v_mov_b32_e32 v85, v93
	v_mov_b32_e32 v110, v85
	v_fma_f32 v85, v111, v113, v173
	v_max_f32_e32 v85, 0xda24260, v85
	s_nop 1
	v_log_f32_e32 v85, v85
	s_nop 0
	v_mul_f32_e32 v93, 0x3f317217, v85
	v_fma_f32 v93, v85, s13, -v93
	v_fmac_f32_e32 v93, 0x3377d1cf, v85
	v_fmac_f32_e32 v93, 0x3f317217, v85
	s_nop 1
	v_mov_b32_e32 v85, v93
	v_mov_b32_e32 v111, v85
	v_max_f32_e32 v85, v78, v78
	v_med3_f32 v85, v85, s39, v195
	v_mul_f32_e32 v85, 0xbfb8aa3b, v85
	v_exp_f32_e32 v112, v85
	s_nop 0
	v_add_f32_e32 v85, 1.0, v112
	v_rcp_f32_e32 v118, v85
	v_max_f32_e32 v85, v79, v79
	v_med3_f32 v85, v85, s39, v195
	v_mul_f32_e32 v85, 0xbfb8aa3b, v85
	v_exp_f32_e32 v113, v85
	s_nop 0
	v_add_f32_e32 v85, 1.0, v113
	v_rcp_f32_e32 v119, v85
	v_fma_f32 v85, v118, v120, v170
	v_max_f32_e32 v85, 0xda24260, v85
	v_pk_mul_f32 v[112:113], v[112:113], v[120:121]
	v_cvt_pk_bf16_f32 v120, v104, v105
	v_log_f32_e32 v85, v85
	v_pk_mul_f32 v[126:127], v[118:119], v[112:113]
	v_cvt_pk_bf16_f32 v118, v96, v97
	v_mul_f32_e32 v93, 0x3f317217, v85
	v_fma_f32 v93, v85, s13, -v93
	v_fmac_f32_e32 v93, 0x3377d1cf, v85
	v_fmac_f32_e32 v93, 0x3f317217, v85
	s_nop 1
	v_mov_b32_e32 v85, v93
	v_mov_b32_e32 v112, v85
	v_fma_f32 v85, v119, v121, v171
	v_max_f32_e32 v85, 0xda24260, v85
	v_cvt_pk_bf16_f32 v119, v102, v103
	v_cvt_pk_bf16_f32 v121, v126, v127
	v_log_f32_e32 v85, v85
	s_nop 0
	v_mul_f32_e32 v93, 0x3f317217, v85
	v_fma_f32 v93, v85, s13, -v93
	v_fmac_f32_e32 v93, 0x3377d1cf, v85
	v_fmac_f32_e32 v93, 0x3f317217, v85
	s_nop 1
	v_mov_b32_e32 v85, v93
	v_readlane_b32 s0, v253, 0
	v_readlane_b32 s1, v253, 1
	v_mov_b32_e32 v113, v85
	v_lshl_add_u64 v[96:97], v[86:87], 1, s[0:1]
	global_store_dwordx4 v[96:97], v[118:121], off
	v_lshl_add_u64 v[96:97], v[86:87], 2, s[2:3]
	s_mov_b64 s[0:1], 0
	global_store_dwordx4 v[96:97], v[74:77], off
	global_store_dwordx4 v[96:97], v[110:113], off offset:16

; __device__ __forceinline__ float silu_f(float x) { return x * __builtin_amdgcn_rcpf(1.f + __expf(-x)); }
; __device__ __forceinline__ v4u pack8(const float (&y)[8]) { return (v4u){pk2(y[0], y[1]), pk2(y[2], y[3]), pk2(y[4], y[5]), pk2(y[6], y[7])}; }
;     __device__ __forceinline__ void operator()(const f32x4 (&acc)[2][2][4][2], const pg8::Unit& u, int wr, int wc, int fr, int fq) const {
;     ...
;                         const int row = lrow0 + ai * 128 + m * 16; const size_t off = (size_t)row * 1024 + c;
;                         const f32x4 v0 = acc[ai][bj][m][0] * rs[ai][m], v1 = acc[ai][bj][m][1] * rs[ai][m];
;                         const float v[8] = {v0[0], v0[1], v0[2], v0[3], v1[0], v1[1], v1[2], v1[3]};
;                         float y[8];
;                         if (region == 0) {
; #pragma unroll
;                             for (int j = 0; j < 8; ++j) y[j] = silu_f(v[j]);
;                             *(v4u*)(o0 + off) = pack8(y);
;                         } else if (region == 1) {
;                             float lf[8];
; #pragma unroll
;                             for (int j = 0; j < 8; ++j) {
;                                 const float om = 1.f - lb[j];
;                                 const float fc = fminf(fmaxf(v[j], -80.f), 80.f);
;                                 const float e = __expf(-fc), sg = __builtin_amdgcn_rcpf(1.f + e);
;                                 y[j] = om * e * sg;
;                                 lf[j] = __logf(fmaxf(lb[j] + om * sg, 1e-30f));
;                             }
;                             *(v4u*)(o1 + off) = pack8(y);
;                             *(f32x4*)(of + off) = (f32x4){lf[0], lf[1], lf[2], lf[3]}; *(f32x4*)(of + off + 4) = (f32x4){lf[4], lf[5], lf[6], lf[7]};
.LBB0_1008:
	v_mov_b32_e32 v169, v168
	v_mov_b32_e32 v86, v168
	v_mov_b32_e32 v87, v168
	v_or_b32_e32 v166, v166, v94
	v_pk_mul_f32 v[78:79], v[64:65], v[86:87]
	v_pk_mul_f32 v[80:81], v[62:63], v[168:169]
	v_pk_mul_f32 v[62:63], v[60:61], v[86:87]
	v_pk_mul_f32 v[64:65], v[58:59], v[168:169]
	s_and_b64 vcc, exec, s[44:45]
	s_mov_b64 s[0:1], -1
	s_cbranch_vccnz .LBB0_1017
	s_and_b64 vcc, exec, s[42:43]
	s_cbranch_vccnz .LBB0_1011
	v_max_f32_e32 v58, v80, v80
	s_mov_b32 s28, 0xc2a00000
	v_med3_f32 v58, v58, s28, v195
	v_mul_f32_e32 v58, 0xbfb8aa3b, v58
	v_exp_f32_e32 v58, v58
	v_pk_add_f32 v[88:89], v[72:73], 1.0 op_sel_hi:[1,0] neg_lo:[1,0] neg_hi:[1,0]
	s_mov_b32 s13, 0x3f317217
	s_mov_b32 s15, 0x7f800000
	v_add_f32_e32 v59, 1.0, v58
	v_rcp_f32_e32 v60, v59
	v_max_f32_e32 v59, v81, v81
	v_med3_f32 v59, v59, s28, v195
	v_mul_f32_e32 v59, 0xbfb8aa3b, v59
	v_exp_f32_e32 v59, v59
	v_pk_add_f32 v[102:103], v[70:71], 1.0 op_sel_hi:[1,0] neg_lo:[1,0] neg_hi:[1,0]
	v_pk_add_f32 v[104:105], v[68:69], 1.0 op_sel_hi:[1,0] neg_lo:[1,0] neg_hi:[1,0]
	v_pk_add_f32 v[112:113], v[66:67], 1.0 op_sel_hi:[1,0] neg_lo:[1,0] neg_hi:[1,0]
	v_add_f32_e32 v61, 1.0, v59
	v_rcp_f32_e32 v61, v61
	v_pk_mul_f32 v[58:59], v[58:59], v[88:89]
	s_nop 0
	v_pk_mul_f32 v[86:87], v[60:61], v[58:59]
	v_fma_f32 v58, v60, v88, v72
	v_max_f32_e32 v58, 0xda24260, v58
	v_cvt_pk_bf16_f32 v86, v86, v87
	s_nop 0
	v_log_f32_e32 v58, v58
	s_nop 0
	v_mul_f32_e32 v59, 0x3f317217, v58
	v_fma_f32 v59, v58, s13, -v59
	v_fmac_f32_e32 v59, 0x3377d1cf, v58
	v_fmac_f32_e32 v59, 0x3f317217, v58
	s_nop 1
	v_mov_b32_e32 v58, v59
	v_fma_f32 v59, v61, v89, v73
	v_max_f32_e32 v59, 0xda24260, v59
	s_nop 1
	v_log_f32_e32 v59, v59
	s_nop 0
	v_mul_f32_e32 v60, 0x3f317217, v59
	v_fma_f32 v60, v59, s13, -v60
	v_fmac_f32_e32 v60, 0x3377d1cf, v59
	v_fmac_f32_e32 v60, 0x3f317217, v59
	s_nop 1
	v_mov_b32_e32 v59, v60
	v_max_f32_e32 v60, v78, v78
	v_med3_f32 v60, v60, s28, v195
	v_mul_f32_e32 v60, 0xbfb8aa3b, v60
	v_exp_f32_e32 v60, v60
	s_nop 0
	v_add_f32_e32 v61, 1.0, v60
	v_rcp_f32_e32 v96, v61
	v_max_f32_e32 v61, v79, v79
	v_med3_f32 v61, v61, s28, v195
	v_mul_f32_e32 v61, 0xbfb8aa3b, v61
	v_exp_f32_e32 v61, v61
	s_nop 0
	v_add_f32_e32 v77, 1.0, v61
	v_rcp_f32_e32 v97, v77
	v_pk_mul_f32 v[60:61], v[60:61], v[102:103]
	s_nop 0
	v_pk_mul_f32 v[88:89], v[96:97], v[60:61]
	v_fma_f32 v60, v96, v102, v70
	v_max_f32_e32 v60, 0xda24260, v60
	v_cvt_pk_bf16_f32 v87, v88, v89
	s_nop 0
	v_log_f32_e32 v60, v60
	s_nop 0
	v_mul_f32_e32 v61, 0x3f317217, v60
	v_fma_f32 v61, v60, s13, -v61
	v_fmac_f32_e32 v61, 0x3377d1cf, v60
	v_fmac_f32_e32 v61, 0x3f317217, v60
	s_nop 1
	v_mov_b32_e32 v60, v61
	v_fma_f32 v61, v97, v103, v71
	v_max_f32_e32 v61, 0xda24260, v61
	s_nop 1
	v_log_f32_e32 v61, v61
	s_nop 0
	v_mul_f32_e32 v77, 0x3f317217, v61
	v_fma_f32 v77, v61, s13, -v77
	v_fmac_f32_e32 v77, 0x3377d1cf, v61
	v_fmac_f32_e32 v77, 0x3f317217, v61
	s_nop 1
	v_mov_b32_e32 v61, v77
	v_max_f32_e32 v77, v64, v64
	v_med3_f32 v77, v77, s28, v195
	v_mul_f32_e32 v77, 0xbfb8aa3b, v77
	v_exp_f32_e32 v96, v77
	s_nop 0
	v_add_f32_e32 v77, 1.0, v96
	v_rcp_f32_e32 v102, v77
	v_max_f32_e32 v77, v65, v65
	v_med3_f32 v77, v77, s28, v195
	v_mul_f32_e32 v77, 0xbfb8aa3b, v77
	v_exp_f32_e32 v97, v77
	s_nop 0
	v_add_f32_e32 v77, 1.0, v97
	v_rcp_f32_e32 v103, v77
	v_fma_f32 v77, v102, v104, v68
	v_max_f32_e32 v77, 0xda24260, v77
	v_pk_mul_f32 v[96:97], v[96:97], v[104:105]
	s_nop 0
	v_log_f32_e32 v77, v77
	v_pk_mul_f32 v[96:97], v[102:103], v[96:97]
	v_mul_f32_e32 v85, 0x3f317217, v77
	v_fma_f32 v85, v77, s13, -v85
	v_fmac_f32_e32 v85, 0x3377d1cf, v77
	v_fmac_f32_e32 v85, 0x3f317217, v77
	v_cvt_pk_bf16_f32 v88, v96, v97
	s_nop 0
	v_mov_b32_e32 v77, v85
	v_mov_b32_e32 v102, v77
	v_fma_f32 v77, v103, v105, v69
	v_max_f32_e32 v77, 0xda24260, v77
	s_nop 1
	v_log_f32_e32 v77, v77
	s_nop 0
	v_mul_f32_e32 v85, 0x3f317217, v77
	v_fma_f32 v85, v77, s13, -v85
	v_fmac_f32_e32 v85, 0x3377d1cf, v77
	v_fmac_f32_e32 v85, 0x3f317217, v77
	s_nop 1
	v_mov_b32_e32 v77, v85
	v_mov_b32_e32 v103, v77
	v_max_f32_e32 v77, v62, v62
	v_med3_f32 v77, v77, s28, v195
	v_mul_f32_e32 v77, 0xbfb8aa3b, v77
	v_exp_f32_e32 v104, v77
	s_nop 0
	v_add_f32_e32 v77, 1.0, v104
	v_rcp_f32_e32 v110, v77
	v_max_f32_e32 v77, v63, v63
	v_med3_f32 v77, v77, s28, v195
	v_mul_f32_e32 v77, 0xbfb8aa3b, v77
	v_exp_f32_e32 v105, v77
	s_nop 0
	v_add_f32_e32 v77, 1.0, v105
	v_rcp_f32_e32 v111, v77
	v_fma_f32 v77, v110, v112, v66
	v_max_f32_e32 v77, 0xda24260, v77
	v_pk_mul_f32 v[104:105], v[104:105], v[112:113]
	s_nop 0
	v_log_f32_e32 v77, v77
	v_pk_mul_f32 v[118:119], v[110:111], v[104:105]
	v_mul_f32_e32 v85, 0x3f317217, v77
	v_fma_f32 v85, v77, s13, -v85
	v_fmac_f32_e32 v85, 0x3377d1cf, v77
	v_fmac_f32_e32 v85, 0x3f317217, v77
	v_cvt_pk_bf16_f32 v89, v118, v119
	s_nop 0
	v_mov_b32_e32 v77, v85
	v_mov_b32_e32 v104, v77
	v_fma_f32 v77, v111, v113, v67
	v_max_f32_e32 v77, 0xda24260, v77
	s_nop 1
	v_log_f32_e32 v77, v77
	s_nop 0
	v_mul_f32_e32 v85, 0x3f317217, v77
	v_fma_f32 v85, v77, s13, -v85
	v_fmac_f32_e32 v85, 0x3377d1cf, v77
	v_fmac_f32_e32 v85, 0x3f317217, v77
	s_nop 1
	v_mov_b32_e32 v77, v85
	v_readlane_b32 s0, v253, 0
	v_readlane_b32 s1, v253, 1
	v_mov_b32_e32 v105, v77
	v_lshl_add_u64 v[96:97], v[166:167], 1, s[0:1]
	global_store_dwordx4 v[96:97], v[86:89], off
	s_mov_b64 s[0:1], 0
	s_nop 0
	v_lshl_add_u64 v[86:87], v[166:167], 2, s[2:3]
	global_store_dwordx4 v[86:87], v[58:61], off
	global_store_dwordx4 v[86:87], v[102:105], off offset:16

; __device__ __forceinline__ float silu_f(float x) { return x * __builtin_amdgcn_rcpf(1.f + __expf(-x)); }
; __device__ __forceinline__ v4u pack8(const float (&y)[8]) { return (v4u){pk2(y[0], y[1]), pk2(y[2], y[3]), pk2(y[4], y[5]), pk2(y[6], y[7])}; }
;     __device__ __forceinline__ void operator()(const f32x4 (&acc)[2][2][4][2], const pg8::Unit& u, int wr, int wc, int fr, int fq) const {
;     ...
;                         const int row = lrow0 + ai * 128 + m * 16; const size_t off = (size_t)row * 1024 + c;
;                         const f32x4 v0 = acc[ai][bj][m][0] * rs[ai][m], v1 = acc[ai][bj][m][1] * rs[ai][m];
;                         const float v[8] = {v0[0], v0[1], v0[2], v0[3], v1[0], v1[1], v1[2], v1[3]};
;                         float y[8];
;                         if (region == 0) {
; #pragma unroll
;                             for (int j = 0; j < 8; ++j) y[j] = silu_f(v[j]);
;                             *(v4u*)(o0 + off) = pack8(y);
;                         } else if (region == 1) {
;                             float lf[8];
; #pragma unroll
;                             for (int j = 0; j < 8; ++j) {
;                                 const float om = 1.f - lb[j];
;                                 const float fc = fminf(fmaxf(v[j], -80.f), 80.f);
;                                 const float e = __expf(-fc), sg = __builtin_amdgcn_rcpf(1.f + e);
;                                 y[j] = om * e * sg;
;                                 lf[j] = __logf(fmaxf(lb[j] + om * sg, 1e-30f));
;                             }
;                             *(v4u*)(o1 + off) = pack8(y);
;                             *(f32x4*)(of + off) = (f32x4){lf[0], lf[1], lf[2], lf[3]}; *(f32x4*)(of + off + 4) = (f32x4){lf[4], lf[5], lf[6], lf[7]};
.LBB0_1019:
	v_mov_b32_e32 v125, v124
	v_mov_b32_e32 v62, v124
	v_mov_b32_e32 v63, v124
	v_or_b32_e32 v122, v122, v94
	v_pk_mul_f32 v[58:59], v[56:57], v[62:63]
	v_pk_mul_f32 v[60:61], v[54:55], v[124:125]
	v_pk_mul_f32 v[54:55], v[52:53], v[62:63]
	v_pk_mul_f32 v[56:57], v[50:51], v[124:125]
	s_and_b64 vcc, exec, s[44:45]
	s_mov_b64 s[0:1], -1
	s_cbranch_vccnz .LBB0_1028
	s_and_b64 vcc, exec, s[42:43]
	s_cbranch_vccnz .LBB0_1022
	v_max_f32_e32 v50, v60, v60
	s_mov_b32 s28, 0xc2a00000
	v_med3_f32 v50, v50, s28, v195
	v_mul_f32_e32 v50, 0xbfb8aa3b, v50
	v_exp_f32_e32 v50, v50
	v_pk_add_f32 v[64:65], v[72:73], 1.0 op_sel_hi:[1,0] neg_lo:[1,0] neg_hi:[1,0]
	s_mov_b32 s13, 0x3f317217
	s_mov_b32 s15, 0x7f800000
	v_add_f32_e32 v51, 1.0, v50
	v_rcp_f32_e32 v52, v51
	v_max_f32_e32 v51, v61, v61
	v_med3_f32 v51, v51, s28, v195
	v_mul_f32_e32 v51, 0xbfb8aa3b, v51
	v_exp_f32_e32 v51, v51
	v_pk_add_f32 v[80:81], v[70:71], 1.0 op_sel_hi:[1,0] neg_lo:[1,0] neg_hi:[1,0]
	v_pk_add_f32 v[86:87], v[68:69], 1.0 op_sel_hi:[1,0] neg_lo:[1,0] neg_hi:[1,0]
	v_pk_add_f32 v[96:97], v[66:67], 1.0 op_sel_hi:[1,0] neg_lo:[1,0] neg_hi:[1,0]
	v_add_f32_e32 v53, 1.0, v51
	v_rcp_f32_e32 v53, v53
	v_pk_mul_f32 v[50:51], v[50:51], v[64:65]
	s_nop 0
	v_pk_mul_f32 v[62:63], v[52:53], v[50:51]
	v_fma_f32 v50, v52, v64, v72
	v_max_f32_e32 v50, 0xda24260, v50
	v_cvt_pk_bf16_f32 v62, v62, v63
	s_nop 0
	v_log_f32_e32 v50, v50
	s_nop 0
	v_mul_f32_e32 v51, 0x3f317217, v50
	v_fma_f32 v51, v50, s13, -v51
	v_fmac_f32_e32 v51, 0x3377d1cf, v50
	v_fmac_f32_e32 v51, 0x3f317217, v50
	s_nop 1
	v_mov_b32_e32 v50, v51
	v_fma_f32 v51, v53, v65, v73
	v_max_f32_e32 v51, 0xda24260, v51
	s_nop 1
	v_log_f32_e32 v51, v51
	s_nop 0
	v_mul_f32_e32 v52, 0x3f317217, v51
	v_fma_f32 v52, v51, s13, -v52
	v_fmac_f32_e32 v52, 0x3377d1cf, v51
	v_fmac_f32_e32 v52, 0x3f317217, v51
	s_nop 1
	v_mov_b32_e32 v51, v52
	v_max_f32_e32 v52, v58, v58
	v_med3_f32 v52, v52, s28, v195
	v_mul_f32_e32 v52, 0xbfb8aa3b, v52
	v_exp_f32_e32 v52, v52
	s_nop 0
	v_add_f32_e32 v53, 1.0, v52
	v_rcp_f32_e32 v78, v53
	v_max_f32_e32 v53, v59, v59
	v_med3_f32 v53, v53, s28, v195
	v_mul_f32_e32 v53, 0xbfb8aa3b, v53
	v_exp_f32_e32 v53, v53
	s_nop 0
	v_add_f32_e32 v64, 1.0, v53
	v_rcp_f32_e32 v79, v64
	v_pk_mul_f32 v[52:53], v[52:53], v[80:81]
	s_nop 0
	v_pk_mul_f32 v[64:65], v[78:79], v[52:53]
	v_fma_f32 v52, v78, v80, v70
	v_max_f32_e32 v52, 0xda24260, v52
	v_cvt_pk_bf16_f32 v63, v64, v65
	s_nop 0
	v_log_f32_e32 v52, v52
	s_nop 0
	v_mul_f32_e32 v53, 0x3f317217, v52
	v_fma_f32 v53, v52, s13, -v53
	v_fmac_f32_e32 v53, 0x3377d1cf, v52
	v_fmac_f32_e32 v53, 0x3f317217, v52
	s_nop 1
	v_mov_b32_e32 v52, v53
	v_fma_f32 v53, v79, v81, v71
	v_max_f32_e32 v53, 0xda24260, v53
	s_nop 1
	v_log_f32_e32 v53, v53
	s_nop 0
	v_mul_f32_e32 v77, 0x3f317217, v53
	v_fma_f32 v77, v53, s13, -v77
	v_fmac_f32_e32 v77, 0x3377d1cf, v53
	v_fmac_f32_e32 v77, 0x3f317217, v53
	s_nop 1
	v_mov_b32_e32 v53, v77
	v_max_f32_e32 v77, v56, v56
	v_med3_f32 v77, v77, s28, v195
	v_mul_f32_e32 v77, 0xbfb8aa3b, v77
	v_exp_f32_e32 v78, v77
	s_nop 0
	v_add_f32_e32 v77, 1.0, v78
	v_rcp_f32_e32 v80, v77
	v_max_f32_e32 v77, v57, v57
	v_med3_f32 v77, v77, s28, v195
	v_mul_f32_e32 v77, 0xbfb8aa3b, v77
	v_exp_f32_e32 v79, v77
	s_nop 0
	v_add_f32_e32 v77, 1.0, v79
	v_rcp_f32_e32 v81, v77
	v_fma_f32 v77, v80, v86, v68
	v_max_f32_e32 v77, 0xda24260, v77
	v_pk_mul_f32 v[78:79], v[78:79], v[86:87]
	v_pk_mul_f32 v[88:89], v[80:81], v[78:79]
	s_nop 0
	v_log_f32_e32 v77, v77
	v_cvt_pk_bf16_f32 v64, v88, v89
	v_mul_f32_e32 v78, 0x3f317217, v77
	v_fma_f32 v78, v77, s13, -v78
	v_fmac_f32_e32 v78, 0x3377d1cf, v77
	v_fmac_f32_e32 v78, 0x3f317217, v77
	s_nop 1
	v_mov_b32_e32 v77, v78
	v_mov_b32_e32 v78, v77
	v_fma_f32 v77, v81, v87, v69
	v_max_f32_e32 v77, 0xda24260, v77
	s_nop 1
	v_log_f32_e32 v77, v77
	s_nop 0
	v_mul_f32_e32 v79, 0x3f317217, v77
	v_fma_f32 v79, v77, s13, -v79
	v_fmac_f32_e32 v79, 0x3377d1cf, v77
	v_fmac_f32_e32 v79, 0x3f317217, v77
	s_nop 1
	v_mov_b32_e32 v77, v79
	v_mov_b32_e32 v79, v77
	v_max_f32_e32 v77, v54, v54
	v_med3_f32 v77, v77, s28, v195
	v_mul_f32_e32 v77, 0xbfb8aa3b, v77
	v_exp_f32_e32 v80, v77
	s_nop 0
	v_add_f32_e32 v77, 1.0, v80
	v_rcp_f32_e32 v86, v77
	v_max_f32_e32 v77, v55, v55
	v_med3_f32 v77, v77, s28, v195
	v_mul_f32_e32 v77, 0xbfb8aa3b, v77
	v_exp_f32_e32 v81, v77
	s_nop 0
	v_add_f32_e32 v77, 1.0, v81
	v_rcp_f32_e32 v87, v77
	v_fma_f32 v77, v86, v96, v66
	v_max_f32_e32 v77, 0xda24260, v77
	v_pk_mul_f32 v[80:81], v[80:81], v[96:97]
	v_pk_mul_f32 v[102:103], v[86:87], v[80:81]
	s_nop 0
	v_log_f32_e32 v77, v77
	v_cvt_pk_bf16_f32 v65, v102, v103
	v_mul_f32_e32 v80, 0x3f317217, v77
	v_fma_f32 v80, v77, s13, -v80
	v_fmac_f32_e32 v80, 0x3377d1cf, v77
	v_fmac_f32_e32 v80, 0x3f317217, v77
	s_nop 1
	v_mov_b32_e32 v77, v80
	v_mov_b32_e32 v80, v77
	v_fma_f32 v77, v87, v97, v67
	v_max_f32_e32 v77, 0xda24260, v77
	s_nop 1
	v_log_f32_e32 v77, v77
	s_nop 0
	v_mul_f32_e32 v81, 0x3f317217, v77
	v_fma_f32 v81, v77, s13, -v81
	v_fmac_f32_e32 v81, 0x3377d1cf, v77
	v_fmac_f32_e32 v81, 0x3f317217, v77
	s_nop 1
	v_mov_b32_e32 v77, v81
	v_readlane_b32 s0, v253, 0
	v_readlane_b32 s1, v253, 1
	v_mov_b32_e32 v81, v77
	v_lshl_add_u64 v[86:87], v[122:123], 1, s[0:1]
	global_store_dwordx4 v[86:87], v[62:65], off
	s_mov_b64 s[0:1], 0
	s_nop 0
	v_lshl_add_u64 v[62:63], v[122:123], 2, s[2:3]
	global_store_dwordx4 v[62:63], v[50:53], off
	global_store_dwordx4 v[62:63], v[78:81], off offset:16

; __device__ __forceinline__ float silu_f(float x) { return x * __builtin_amdgcn_rcpf(1.f + __expf(-x)); }
; __device__ __forceinline__ v4u pack8(const float (&y)[8]) { return (v4u){pk2(y[0], y[1]), pk2(y[2], y[3]), pk2(y[4], y[5]), pk2(y[6], y[7])}; }
;     __device__ __forceinline__ void operator()(const f32x4 (&acc)[2][2][4][2], const pg8::Unit& u, int wr, int wc, int fr, int fq) const {
;     ...
;                         const int row = lrow0 + ai * 128 + m * 16; const size_t off = (size_t)row * 1024 + c;
;                         const f32x4 v0 = acc[ai][bj][m][0] * rs[ai][m], v1 = acc[ai][bj][m][1] * rs[ai][m];
;                         const float v[8] = {v0[0], v0[1], v0[2], v0[3], v1[0], v1[1], v1[2], v1[3]};
;                         float y[8];
;                         if (region == 0) {
; #pragma unroll
;                             for (int j = 0; j < 8; ++j) y[j] = silu_f(v[j]);
;                             *(v4u*)(o0 + off) = pack8(y);
;                         } else if (region == 1) {
;                             float lf[8];
; #pragma unroll
;                             for (int j = 0; j < 8; ++j) {
;                                 const float om = 1.f - lb[j];
;                                 const float fc = fminf(fmaxf(v[j], -80.f), 80.f);
;                                 const float e = __expf(-fc), sg = __builtin_amdgcn_rcpf(1.f + e);
;                                 y[j] = om * e * sg;
;                                 lf[j] = __logf(fmaxf(lb[j] + om * sg, 1e-30f));
;                             }
;                             *(v4u*)(o1 + off) = pack8(y);
;                             *(f32x4*)(of + off) = (f32x4){lf[0], lf[1], lf[2], lf[3]}; *(f32x4*)(of + off + 4) = (f32x4){lf[4], lf[5], lf[6], lf[7]};
.LBB0_1030:
	v_mov_b32_e32 v117, v116
	v_mov_b32_e32 v54, v116
	v_mov_b32_e32 v55, v116
	v_or_b32_e32 v114, v114, v94
	v_pk_mul_f32 v[50:51], v[48:49], v[54:55]
	v_pk_mul_f32 v[52:53], v[46:47], v[116:117]
	v_pk_mul_f32 v[46:47], v[44:45], v[54:55]
	v_pk_mul_f32 v[48:49], v[42:43], v[116:117]
	s_and_b64 vcc, exec, s[44:45]
	s_mov_b64 s[0:1], -1
	s_cbranch_vccnz .LBB0_1039
	s_and_b64 vcc, exec, s[42:43]
	s_cbranch_vccnz .LBB0_1033
	v_max_f32_e32 v42, v52, v52
	s_mov_b32 s28, 0xc2a00000
	v_med3_f32 v42, v42, s28, v195
	v_mul_f32_e32 v42, 0xbfb8aa3b, v42
	v_exp_f32_e32 v42, v42
	v_pk_add_f32 v[56:57], v[72:73], 1.0 op_sel_hi:[1,0] neg_lo:[1,0] neg_hi:[1,0]
	s_mov_b32 s13, 0x3f317217
	s_mov_b32 s15, 0x7f800000
	v_add_f32_e32 v43, 1.0, v42
	v_rcp_f32_e32 v44, v43
	v_max_f32_e32 v43, v53, v53
	v_med3_f32 v43, v43, s28, v195
	v_mul_f32_e32 v43, 0xbfb8aa3b, v43
	v_exp_f32_e32 v43, v43
	v_pk_add_f32 v[60:61], v[70:71], 1.0 op_sel_hi:[1,0] neg_lo:[1,0] neg_hi:[1,0]
	v_pk_add_f32 v[62:63], v[68:69], 1.0 op_sel_hi:[1,0] neg_lo:[1,0] neg_hi:[1,0]
	v_pk_add_f32 v[78:79], v[66:67], 1.0 op_sel_hi:[1,0] neg_lo:[1,0] neg_hi:[1,0]
	v_add_f32_e32 v45, 1.0, v43
	v_rcp_f32_e32 v45, v45
	v_pk_mul_f32 v[42:43], v[42:43], v[56:57]
	s_nop 0
	v_pk_mul_f32 v[54:55], v[44:45], v[42:43]
	v_fma_f32 v42, v44, v56, v72
	v_max_f32_e32 v42, 0xda24260, v42
	v_cvt_pk_bf16_f32 v54, v54, v55
	s_nop 0
	v_log_f32_e32 v42, v42
	s_nop 0
	v_mul_f32_e32 v43, 0x3f317217, v42
	v_fma_f32 v43, v42, s13, -v43
	v_fmac_f32_e32 v43, 0x3377d1cf, v42
	v_fmac_f32_e32 v43, 0x3f317217, v42
	s_nop 1
	v_mov_b32_e32 v42, v43
	v_fma_f32 v43, v45, v57, v73
	v_max_f32_e32 v43, 0xda24260, v43
	s_nop 1
	v_log_f32_e32 v43, v43
	s_nop 0
	v_mul_f32_e32 v44, 0x3f317217, v43
	v_fma_f32 v44, v43, s13, -v44
	v_fmac_f32_e32 v44, 0x3377d1cf, v43
	v_fmac_f32_e32 v44, 0x3f317217, v43
	s_nop 1
	v_mov_b32_e32 v43, v44
	v_max_f32_e32 v44, v50, v50
	v_med3_f32 v44, v44, s28, v195
	v_mul_f32_e32 v44, 0xbfb8aa3b, v44
	v_exp_f32_e32 v44, v44
	s_nop 0
	v_add_f32_e32 v45, 1.0, v44
	v_rcp_f32_e32 v58, v45
	v_max_f32_e32 v45, v51, v51
	v_med3_f32 v45, v45, s28, v195
	v_mul_f32_e32 v45, 0xbfb8aa3b, v45
	v_exp_f32_e32 v45, v45
	s_nop 0
	v_add_f32_e32 v56, 1.0, v45
	v_rcp_f32_e32 v59, v56
	v_pk_mul_f32 v[44:45], v[44:45], v[60:61]
	s_nop 0
	v_pk_mul_f32 v[56:57], v[58:59], v[44:45]
	v_fma_f32 v44, v58, v60, v70
	v_max_f32_e32 v44, 0xda24260, v44
	v_cvt_pk_bf16_f32 v55, v56, v57
	s_nop 0
	v_log_f32_e32 v44, v44
	s_nop 0
	v_mul_f32_e32 v45, 0x3f317217, v44
	v_fma_f32 v45, v44, s13, -v45
	v_fmac_f32_e32 v45, 0x3377d1cf, v44
	v_fmac_f32_e32 v45, 0x3f317217, v44
	s_nop 1
	v_mov_b32_e32 v44, v45
	v_fma_f32 v45, v59, v61, v71
	v_max_f32_e32 v45, 0xda24260, v45
	s_nop 1
	v_log_f32_e32 v45, v45
	s_nop 0
	v_mul_f32_e32 v58, 0x3f317217, v45
	v_fma_f32 v58, v45, s13, -v58
	v_fmac_f32_e32 v58, 0x3377d1cf, v45
	v_fmac_f32_e32 v58, 0x3f317217, v45
	s_nop 1
	v_mov_b32_e32 v45, v58
	v_max_f32_e32 v58, v48, v48
	v_med3_f32 v58, v58, s28, v195
	v_mul_f32_e32 v58, 0xbfb8aa3b, v58
	v_exp_f32_e32 v58, v58
	s_nop 0
	v_add_f32_e32 v59, 1.0, v58
	v_rcp_f32_e32 v60, v59
	v_max_f32_e32 v59, v49, v49
	v_med3_f32 v59, v59, s28, v195
	v_mul_f32_e32 v59, 0xbfb8aa3b, v59
	v_exp_f32_e32 v59, v59
	s_nop 0
	v_add_f32_e32 v61, 1.0, v59
	v_rcp_f32_e32 v61, v61
	v_pk_mul_f32 v[58:59], v[58:59], v[62:63]
	s_nop 0
	v_pk_mul_f32 v[64:65], v[60:61], v[58:59]
	v_fma_f32 v58, v60, v62, v68
	v_max_f32_e32 v58, 0xda24260, v58
	v_cvt_pk_bf16_f32 v56, v64, v65
	s_nop 0
	v_log_f32_e32 v58, v58
	s_nop 0
	v_mul_f32_e32 v59, 0x3f317217, v58
	v_fma_f32 v59, v58, s13, -v59
	v_fmac_f32_e32 v59, 0x3377d1cf, v58
	v_fmac_f32_e32 v59, 0x3f317217, v58
	s_nop 1
	v_mov_b32_e32 v58, v59
	v_fma_f32 v59, v61, v63, v69
	v_max_f32_e32 v59, 0xda24260, v59
	s_nop 1
	v_log_f32_e32 v59, v59
	s_nop 0
	v_mul_f32_e32 v60, 0x3f317217, v59
	v_fma_f32 v60, v59, s13, -v60
	v_fmac_f32_e32 v60, 0x3377d1cf, v59
	v_fmac_f32_e32 v60, 0x3f317217, v59
	s_nop 1
	v_mov_b32_e32 v59, v60
	v_max_f32_e32 v60, v46, v46
	v_med3_f32 v60, v60, s28, v195
	v_mul_f32_e32 v60, 0xbfb8aa3b, v60
	v_exp_f32_e32 v60, v60
	s_nop 0
	v_add_f32_e32 v61, 1.0, v60
	v_rcp_f32_e32 v62, v61
	v_max_f32_e32 v61, v47, v47
	v_med3_f32 v61, v61, s28, v195
	v_mul_f32_e32 v61, 0xbfb8aa3b, v61
	v_exp_f32_e32 v61, v61
	s_nop 0
	v_add_f32_e32 v63, 1.0, v61
	v_rcp_f32_e32 v63, v63
	v_pk_mul_f32 v[60:61], v[60:61], v[78:79]
	s_nop 0
	v_pk_mul_f32 v[80:81], v[62:63], v[60:61]
	v_fma_f32 v60, v62, v78, v66
	v_max_f32_e32 v60, 0xda24260, v60
	v_cvt_pk_bf16_f32 v57, v80, v81
	s_nop 0
	v_log_f32_e32 v60, v60
	s_nop 0
	v_mul_f32_e32 v61, 0x3f317217, v60
	v_fma_f32 v61, v60, s13, -v61
	v_fmac_f32_e32 v61, 0x3377d1cf, v60
	v_fmac_f32_e32 v61, 0x3f317217, v60
	s_nop 1
	v_mov_b32_e32 v60, v61
	v_fma_f32 v61, v63, v79, v67
	v_max_f32_e32 v61, 0xda24260, v61
	s_nop 1
	v_log_f32_e32 v61, v61
	s_nop 0
	v_mul_f32_e32 v62, 0x3f317217, v61
	v_fma_f32 v62, v61, s13, -v62
	v_fmac_f32_e32 v62, 0x3377d1cf, v61
	v_fmac_f32_e32 v62, 0x3f317217, v61
	s_nop 1
	v_mov_b32_e32 v61, v62
	v_readlane_b32 s0, v253, 0
	v_readlane_b32 s1, v253, 1
	s_nop 0
	v_lshl_add_u64 v[62:63], v[114:115], 1, s[0:1]
	global_store_dwordx4 v[62:63], v[54:57], off
	s_mov_b64 s[0:1], 0
	s_nop 0
	v_lshl_add_u64 v[54:55], v[114:115], 2, s[2:3]
	global_store_dwordx4 v[54:55], v[42:45], off
	global_store_dwordx4 v[54:55], v[58:61], off offset:16

; __device__ __forceinline__ float silu_f(float x) { return x * __builtin_amdgcn_rcpf(1.f + __expf(-x)); }
; __device__ __forceinline__ v4u pack8(const float (&y)[8]) { return (v4u){pk2(y[0], y[1]), pk2(y[2], y[3]), pk2(y[4], y[5]), pk2(y[6], y[7])}; }
;     __device__ __forceinline__ void operator()(const f32x4 (&acc)[2][2][4][2], const pg8::Unit& u, int wr, int wc, int fr, int fq) const {
;     ...
;                         const int row = lrow0 + ai * 128 + m * 16; const size_t off = (size_t)row * 1024 + c;
;                         const f32x4 v0 = acc[ai][bj][m][0] * rs[ai][m], v1 = acc[ai][bj][m][1] * rs[ai][m];
;                         const float v[8] = {v0[0], v0[1], v0[2], v0[3], v1[0], v1[1], v1[2], v1[3]};
;                         float y[8];
;                         if (region == 0) {
; #pragma unroll
;                             for (int j = 0; j < 8; ++j) y[j] = silu_f(v[j]);
;                             *(v4u*)(o0 + off) = pack8(y);
;                         } else if (region == 1) {
;                             float lf[8];
; #pragma unroll
;                             for (int j = 0; j < 8; ++j) {
;                                 const float om = 1.f - lb[j];
;                                 const float fc = fminf(fmaxf(v[j], -80.f), 80.f);
;                                 const float e = __expf(-fc), sg = __builtin_amdgcn_rcpf(1.f + e);
;                                 y[j] = om * e * sg;
;                                 lf[j] = __logf(fmaxf(lb[j] + om * sg, 1e-30f));
;                             }
;                             *(v4u*)(o1 + off) = pack8(y);
;                             *(f32x4*)(of + off) = (f32x4){lf[0], lf[1], lf[2], lf[3]}; *(f32x4*)(of + off + 4) = (f32x4){lf[4], lf[5], lf[6], lf[7]};
.LBB0_1041:
	v_mov_b32_e32 v109, v108
	v_mov_b32_e32 v46, v108
	v_mov_b32_e32 v47, v108
	v_or_b32_e32 v106, v106, v94
	v_pk_mul_f32 v[42:43], v[40:41], v[46:47]
	v_pk_mul_f32 v[44:45], v[38:39], v[108:109]
	v_pk_mul_f32 v[38:39], v[36:37], v[46:47]
	v_pk_mul_f32 v[40:41], v[34:35], v[108:109]
	s_and_b64 vcc, exec, s[44:45]
	s_mov_b64 s[0:1], -1
	s_cbranch_vccnz .LBB0_1050
	s_and_b64 vcc, exec, s[42:43]
	s_cbranch_vccnz .LBB0_1044
	v_max_f32_e32 v34, v44, v44
	s_mov_b32 s28, 0xc2a00000
	v_med3_f32 v34, v34, s28, v195
	v_mul_f32_e32 v34, 0xbfb8aa3b, v34
	v_exp_f32_e32 v34, v34
	v_pk_add_f32 v[48:49], v[72:73], 1.0 op_sel_hi:[1,0] neg_lo:[1,0] neg_hi:[1,0]
	s_mov_b32 s13, 0x3f317217
	s_mov_b32 s15, 0x7f800000
	v_add_f32_e32 v35, 1.0, v34
	v_rcp_f32_e32 v36, v35
	v_max_f32_e32 v35, v45, v45
	v_med3_f32 v35, v35, s28, v195
	v_mul_f32_e32 v35, 0xbfb8aa3b, v35
	v_exp_f32_e32 v35, v35
	v_pk_add_f32 v[52:53], v[70:71], 1.0 op_sel_hi:[1,0] neg_lo:[1,0] neg_hi:[1,0]
	v_pk_add_f32 v[54:55], v[68:69], 1.0 op_sel_hi:[1,0] neg_lo:[1,0] neg_hi:[1,0]
	v_pk_add_f32 v[58:59], v[66:67], 1.0 op_sel_hi:[1,0] neg_lo:[1,0] neg_hi:[1,0]
	v_add_f32_e32 v37, 1.0, v35
	v_rcp_f32_e32 v37, v37
	v_pk_mul_f32 v[34:35], v[34:35], v[48:49]
	s_nop 0
	v_pk_mul_f32 v[46:47], v[36:37], v[34:35]
	v_fma_f32 v34, v36, v48, v72
	v_max_f32_e32 v34, 0xda24260, v34
	v_cvt_pk_bf16_f32 v46, v46, v47
	s_nop 0
	v_log_f32_e32 v34, v34
	s_nop 0
	v_mul_f32_e32 v35, 0x3f317217, v34
	v_fma_f32 v35, v34, s13, -v35
	v_fmac_f32_e32 v35, 0x3377d1cf, v34
	v_fmac_f32_e32 v35, 0x3f317217, v34
	s_nop 1
	v_mov_b32_e32 v34, v35
	v_fma_f32 v35, v37, v49, v73
	v_max_f32_e32 v35, 0xda24260, v35
	s_nop 1
	v_log_f32_e32 v35, v35
	s_nop 0
	v_mul_f32_e32 v36, 0x3f317217, v35
	v_fma_f32 v36, v35, s13, -v36
	v_fmac_f32_e32 v36, 0x3377d1cf, v35
	v_fmac_f32_e32 v36, 0x3f317217, v35
	s_nop 1
	v_mov_b32_e32 v35, v36
	v_max_f32_e32 v36, v42, v42
	v_med3_f32 v36, v36, s28, v195
	v_mul_f32_e32 v36, 0xbfb8aa3b, v36
	v_exp_f32_e32 v36, v36
	s_nop 0
	v_add_f32_e32 v37, 1.0, v36
	v_rcp_f32_e32 v50, v37
	v_max_f32_e32 v37, v43, v43
	v_med3_f32 v37, v37, s28, v195
	v_mul_f32_e32 v37, 0xbfb8aa3b, v37
	v_exp_f32_e32 v37, v37
	s_nop 0
	v_add_f32_e32 v48, 1.0, v37
	v_rcp_f32_e32 v51, v48
	v_pk_mul_f32 v[36:37], v[36:37], v[52:53]
	s_nop 0
	v_pk_mul_f32 v[48:49], v[50:51], v[36:37]
	v_fma_f32 v36, v50, v52, v70
	v_max_f32_e32 v36, 0xda24260, v36
	v_cvt_pk_bf16_f32 v47, v48, v49
	s_nop 0
	v_log_f32_e32 v36, v36
	s_nop 0
	v_mul_f32_e32 v37, 0x3f317217, v36
	v_fma_f32 v37, v36, s13, -v37
	v_fmac_f32_e32 v37, 0x3377d1cf, v36
	v_fmac_f32_e32 v37, 0x3f317217, v36
	s_nop 1
	v_mov_b32_e32 v36, v37
	v_fma_f32 v37, v51, v53, v71
	v_max_f32_e32 v37, 0xda24260, v37
	s_nop 1
	v_log_f32_e32 v37, v37
	s_nop 0
	v_mul_f32_e32 v50, 0x3f317217, v37
	v_fma_f32 v50, v37, s13, -v50
	v_fmac_f32_e32 v50, 0x3377d1cf, v37
	v_fmac_f32_e32 v50, 0x3f317217, v37
	s_nop 1
	v_mov_b32_e32 v37, v50
	v_max_f32_e32 v50, v40, v40
	v_med3_f32 v50, v50, s28, v195
	v_mul_f32_e32 v50, 0xbfb8aa3b, v50
	v_exp_f32_e32 v50, v50
	s_nop 0
	v_add_f32_e32 v51, 1.0, v50
	v_rcp_f32_e32 v52, v51
	v_max_f32_e32 v51, v41, v41
	v_med3_f32 v51, v51, s28, v195
	v_mul_f32_e32 v51, 0xbfb8aa3b, v51
	v_exp_f32_e32 v51, v51
	s_nop 0
	v_add_f32_e32 v53, 1.0, v51
	v_rcp_f32_e32 v53, v53
	v_pk_mul_f32 v[50:51], v[50:51], v[54:55]
	s_nop 0
	v_pk_mul_f32 v[56:57], v[52:53], v[50:51]
	v_fma_f32 v50, v52, v54, v68
	v_max_f32_e32 v50, 0xda24260, v50
	v_cvt_pk_bf16_f32 v48, v56, v57
	s_nop 0
	v_log_f32_e32 v50, v50
	s_nop 0
	v_mul_f32_e32 v51, 0x3f317217, v50
	v_fma_f32 v51, v50, s13, -v51
	v_fmac_f32_e32 v51, 0x3377d1cf, v50
	v_fmac_f32_e32 v51, 0x3f317217, v50
	s_nop 1
	v_mov_b32_e32 v50, v51
	v_fma_f32 v51, v53, v55, v69
	v_max_f32_e32 v51, 0xda24260, v51
	s_nop 1
	v_log_f32_e32 v51, v51
	s_nop 0
	v_mul_f32_e32 v52, 0x3f317217, v51
	v_fma_f32 v52, v51, s13, -v52
	v_fmac_f32_e32 v52, 0x3377d1cf, v51
	v_fmac_f32_e32 v52, 0x3f317217, v51
	s_nop 1
	v_mov_b32_e32 v51, v52
	v_max_f32_e32 v52, v38, v38
	v_med3_f32 v52, v52, s28, v195
	v_mul_f32_e32 v52, 0xbfb8aa3b, v52
	v_exp_f32_e32 v52, v52
	s_nop 0
	v_add_f32_e32 v53, 1.0, v52
	v_rcp_f32_e32 v54, v53
	v_max_f32_e32 v53, v39, v39
	v_med3_f32 v53, v53, s28, v195
	v_mul_f32_e32 v53, 0xbfb8aa3b, v53
	v_exp_f32_e32 v53, v53
	s_nop 0
	v_add_f32_e32 v55, 1.0, v53
	v_rcp_f32_e32 v55, v55
	v_pk_mul_f32 v[52:53], v[52:53], v[58:59]
	s_nop 0
	v_pk_mul_f32 v[60:61], v[54:55], v[52:53]
	v_fma_f32 v52, v54, v58, v66
	v_max_f32_e32 v52, 0xda24260, v52
	v_cvt_pk_bf16_f32 v49, v60, v61
	s_nop 0
	v_log_f32_e32 v52, v52
	s_nop 0
	v_mul_f32_e32 v53, 0x3f317217, v52
	v_fma_f32 v53, v52, s13, -v53
	v_fmac_f32_e32 v53, 0x3377d1cf, v52
	v_fmac_f32_e32 v53, 0x3f317217, v52
	s_nop 1
	v_mov_b32_e32 v52, v53
	v_fma_f32 v53, v55, v59, v67
	v_max_f32_e32 v53, 0xda24260, v53
	s_nop 1
	v_log_f32_e32 v53, v53
	s_nop 0
	v_mul_f32_e32 v54, 0x3f317217, v53
	v_fma_f32 v54, v53, s13, -v54
	v_fmac_f32_e32 v54, 0x3377d1cf, v53
	v_fmac_f32_e32 v54, 0x3f317217, v53
	s_nop 1
	v_mov_b32_e32 v53, v54
	v_readlane_b32 s0, v253, 0
	v_readlane_b32 s1, v253, 1
	s_nop 0
	v_lshl_add_u64 v[54:55], v[106:107], 1, s[0:1]
	global_store_dwordx4 v[54:55], v[46:49], off
	s_mov_b64 s[0:1], 0
	s_nop 0
	v_lshl_add_u64 v[46:47], v[106:107], 2, s[2:3]
	global_store_dwordx4 v[46:47], v[34:37], off
	global_store_dwordx4 v[46:47], v[50:53], off offset:16

; __device__ __forceinline__ float silu_f(float x) { return x * __builtin_amdgcn_rcpf(1.f + __expf(-x)); }
; __device__ __forceinline__ v4u pack8(const float (&y)[8]) { return (v4u){pk2(y[0], y[1]), pk2(y[2], y[3]), pk2(y[4], y[5]), pk2(y[6], y[7])}; }
;     __device__ __forceinline__ void operator()(const f32x4 (&acc)[2][2][4][2], const pg8::Unit& u, int wr, int wc, int fr, int fq) const {
;     ...
;                         const int row = lrow0 + ai * 128 + m * 16; const size_t off = (size_t)row * 1024 + c;
;                         const f32x4 v0 = acc[ai][bj][m][0] * rs[ai][m], v1 = acc[ai][bj][m][1] * rs[ai][m];
;                         const float v[8] = {v0[0], v0[1], v0[2], v0[3], v1[0], v1[1], v1[2], v1[3]};
;                         float y[8];
;                         if (region == 0) {
; #pragma unroll
;                             for (int j = 0; j < 8; ++j) y[j] = silu_f(v[j]);
;                             *(v4u*)(o0 + off) = pack8(y);
;                         } else if (region == 1) {
;                             float lf[8];
; #pragma unroll
;                             for (int j = 0; j < 8; ++j) {
;                                 const float om = 1.f - lb[j];
;                                 const float fc = fminf(fmaxf(v[j], -80.f), 80.f);
;                                 const float e = __expf(-fc), sg = __builtin_amdgcn_rcpf(1.f + e);
;                                 y[j] = om * e * sg;
;                                 lf[j] = __logf(fmaxf(lb[j] + om * sg, 1e-30f));
;                             }
;                             *(v4u*)(o1 + off) = pack8(y);
;                             *(f32x4*)(of + off) = (f32x4){lf[0], lf[1], lf[2], lf[3]}; *(f32x4*)(of + off + 4) = (f32x4){lf[4], lf[5], lf[6], lf[7]};
.LBB0_1052:
	v_mov_b32_e32 v101, v100
	v_mov_b32_e32 v38, v100
	v_mov_b32_e32 v39, v100
	v_or_b32_e32 v98, v98, v94
	v_pk_mul_f32 v[34:35], v[32:33], v[38:39]
	v_pk_mul_f32 v[36:37], v[30:31], v[100:101]
	v_pk_mul_f32 v[30:31], v[28:29], v[38:39]
	v_pk_mul_f32 v[32:33], v[26:27], v[100:101]
	s_and_b64 vcc, exec, s[44:45]
	s_mov_b64 s[0:1], -1
	s_cbranch_vccnz .LBB0_1061
	s_and_b64 vcc, exec, s[42:43]
	s_cbranch_vccnz .LBB0_1055
	v_max_f32_e32 v26, v36, v36
	s_mov_b32 s28, 0xc2a00000
	v_med3_f32 v26, v26, s28, v195
	v_mul_f32_e32 v26, 0xbfb8aa3b, v26
	v_exp_f32_e32 v26, v26
	v_pk_add_f32 v[40:41], v[72:73], 1.0 op_sel_hi:[1,0] neg_lo:[1,0] neg_hi:[1,0]
	s_mov_b32 s13, 0x3f317217
	s_mov_b32 s15, 0x7f800000
	v_add_f32_e32 v27, 1.0, v26
	v_rcp_f32_e32 v28, v27
	v_max_f32_e32 v27, v37, v37
	v_med3_f32 v27, v27, s28, v195
	v_mul_f32_e32 v27, 0xbfb8aa3b, v27
	v_exp_f32_e32 v27, v27
	v_pk_add_f32 v[44:45], v[70:71], 1.0 op_sel_hi:[1,0] neg_lo:[1,0] neg_hi:[1,0]
	v_pk_add_f32 v[46:47], v[68:69], 1.0 op_sel_hi:[1,0] neg_lo:[1,0] neg_hi:[1,0]
	v_pk_add_f32 v[50:51], v[66:67], 1.0 op_sel_hi:[1,0] neg_lo:[1,0] neg_hi:[1,0]
	v_add_f32_e32 v29, 1.0, v27
	v_rcp_f32_e32 v29, v29
	v_pk_mul_f32 v[26:27], v[26:27], v[40:41]
	s_nop 0
	v_pk_mul_f32 v[38:39], v[28:29], v[26:27]
	v_fma_f32 v26, v28, v40, v72
	v_max_f32_e32 v26, 0xda24260, v26
	v_cvt_pk_bf16_f32 v38, v38, v39
	s_nop 0
	v_log_f32_e32 v26, v26
	s_nop 0
	v_mul_f32_e32 v27, 0x3f317217, v26
	v_fma_f32 v27, v26, s13, -v27
	v_fmac_f32_e32 v27, 0x3377d1cf, v26
	v_fmac_f32_e32 v27, 0x3f317217, v26
	s_nop 1
	v_mov_b32_e32 v26, v27
	v_fma_f32 v27, v29, v41, v73
	v_max_f32_e32 v27, 0xda24260, v27
	s_nop 1
	v_log_f32_e32 v27, v27
	s_nop 0
	v_mul_f32_e32 v28, 0x3f317217, v27
	v_fma_f32 v28, v27, s13, -v28
	v_fmac_f32_e32 v28, 0x3377d1cf, v27
	v_fmac_f32_e32 v28, 0x3f317217, v27
	s_nop 1
	v_mov_b32_e32 v27, v28
	v_max_f32_e32 v28, v34, v34
	v_med3_f32 v28, v28, s28, v195
	v_mul_f32_e32 v28, 0xbfb8aa3b, v28
	v_exp_f32_e32 v28, v28
	s_nop 0
	v_add_f32_e32 v29, 1.0, v28
	v_rcp_f32_e32 v42, v29
	v_max_f32_e32 v29, v35, v35
	v_med3_f32 v29, v29, s28, v195
	v_mul_f32_e32 v29, 0xbfb8aa3b, v29
	v_exp_f32_e32 v29, v29
	s_nop 0
	v_add_f32_e32 v40, 1.0, v29
	v_rcp_f32_e32 v43, v40
	v_pk_mul_f32 v[28:29], v[28:29], v[44:45]
	s_nop 0
	v_pk_mul_f32 v[40:41], v[42:43], v[28:29]
	v_fma_f32 v28, v42, v44, v70
	v_max_f32_e32 v28, 0xda24260, v28
	v_cvt_pk_bf16_f32 v39, v40, v41
	s_nop 0
	v_log_f32_e32 v28, v28
	s_nop 0
	v_mul_f32_e32 v29, 0x3f317217, v28
	v_fma_f32 v29, v28, s13, -v29
	v_fmac_f32_e32 v29, 0x3377d1cf, v28
	v_fmac_f32_e32 v29, 0x3f317217, v28
	s_nop 1
	v_mov_b32_e32 v28, v29
	v_fma_f32 v29, v43, v45, v71
	v_max_f32_e32 v29, 0xda24260, v29
	s_nop 1
	v_log_f32_e32 v29, v29
	s_nop 0
	v_mul_f32_e32 v42, 0x3f317217, v29
	v_fma_f32 v42, v29, s13, -v42
	v_fmac_f32_e32 v42, 0x3377d1cf, v29
	v_fmac_f32_e32 v42, 0x3f317217, v29
	s_nop 1
	v_mov_b32_e32 v29, v42
	v_max_f32_e32 v42, v32, v32
	v_med3_f32 v42, v42, s28, v195
	v_mul_f32_e32 v42, 0xbfb8aa3b, v42
	v_exp_f32_e32 v42, v42
	s_nop 0
	v_add_f32_e32 v43, 1.0, v42
	v_rcp_f32_e32 v44, v43
	v_max_f32_e32 v43, v33, v33
	v_med3_f32 v43, v43, s28, v195
	v_mul_f32_e32 v43, 0xbfb8aa3b, v43
	v_exp_f32_e32 v43, v43
	s_nop 0
	v_add_f32_e32 v45, 1.0, v43
	v_rcp_f32_e32 v45, v45
	v_pk_mul_f32 v[42:43], v[42:43], v[46:47]
	s_nop 0
	v_pk_mul_f32 v[48:49], v[44:45], v[42:43]
	v_fma_f32 v42, v44, v46, v68
	v_max_f32_e32 v42, 0xda24260, v42
	v_cvt_pk_bf16_f32 v40, v48, v49
	s_nop 0
	v_log_f32_e32 v42, v42
	s_nop 0
	v_mul_f32_e32 v43, 0x3f317217, v42
	v_fma_f32 v43, v42, s13, -v43
	v_fmac_f32_e32 v43, 0x3377d1cf, v42
	v_fmac_f32_e32 v43, 0x3f317217, v42
	s_nop 1
	v_mov_b32_e32 v42, v43
	v_fma_f32 v43, v45, v47, v69
	v_max_f32_e32 v43, 0xda24260, v43
	s_nop 1
	v_log_f32_e32 v43, v43
	s_nop 0
	v_mul_f32_e32 v44, 0x3f317217, v43
	v_fma_f32 v44, v43, s13, -v44
	v_fmac_f32_e32 v44, 0x3377d1cf, v43
	v_fmac_f32_e32 v44, 0x3f317217, v43
	s_nop 1
	v_mov_b32_e32 v43, v44
	v_max_f32_e32 v44, v30, v30
	v_med3_f32 v44, v44, s28, v195
	v_mul_f32_e32 v44, 0xbfb8aa3b, v44
	v_exp_f32_e32 v44, v44
	s_nop 0
	v_add_f32_e32 v45, 1.0, v44
	v_rcp_f32_e32 v46, v45
	v_max_f32_e32 v45, v31, v31
	v_med3_f32 v45, v45, s28, v195
	v_mul_f32_e32 v45, 0xbfb8aa3b, v45
	v_exp_f32_e32 v45, v45
	s_nop 0
	v_add_f32_e32 v47, 1.0, v45
	v_rcp_f32_e32 v47, v47
	v_pk_mul_f32 v[44:45], v[44:45], v[50:51]
	s_nop 0
	v_pk_mul_f32 v[52:53], v[46:47], v[44:45]
	v_fma_f32 v44, v46, v50, v66
	v_max_f32_e32 v44, 0xda24260, v44
	v_cvt_pk_bf16_f32 v41, v52, v53
	s_nop 0
	v_log_f32_e32 v44, v44
	s_nop 0
	v_mul_f32_e32 v45, 0x3f317217, v44
	v_fma_f32 v45, v44, s13, -v45
	v_fmac_f32_e32 v45, 0x3377d1cf, v44
	v_fmac_f32_e32 v45, 0x3f317217, v44
	s_nop 1
	v_mov_b32_e32 v44, v45
	v_fma_f32 v45, v47, v51, v67
	v_max_f32_e32 v45, 0xda24260, v45
	s_nop 1
	v_log_f32_e32 v45, v45
	s_nop 0
	v_mul_f32_e32 v46, 0x3f317217, v45
	v_fma_f32 v46, v45, s13, -v46
	v_fmac_f32_e32 v46, 0x3377d1cf, v45
	v_fmac_f32_e32 v46, 0x3f317217, v45
	s_nop 1
	v_mov_b32_e32 v45, v46
	v_readlane_b32 s0, v253, 0
	v_readlane_b32 s1, v253, 1
	s_nop 0
	v_lshl_add_u64 v[46:47], v[98:99], 1, s[0:1]
	global_store_dwordx4 v[46:47], v[38:41], off
	s_mov_b64 s[0:1], 0
	s_nop 0
	v_lshl_add_u64 v[38:39], v[98:99], 2, s[2:3]
	global_store_dwordx4 v[38:39], v[26:29], off
	global_store_dwordx4 v[38:39], v[42:45], off offset:16

; __device__ __forceinline__ float silu_f(float x) { return x * __builtin_amdgcn_rcpf(1.f + __expf(-x)); }
; __device__ __forceinline__ v4u pack8(const float (&y)[8]) { return (v4u){pk2(y[0], y[1]), pk2(y[2], y[3]), pk2(y[4], y[5]), pk2(y[6], y[7])}; }
;     __device__ __forceinline__ void operator()(const f32x4 (&acc)[2][2][4][2], const pg8::Unit& u, int wr, int wc, int fr, int fq) const {
;     ...
;                         const int row = lrow0 + ai * 128 + m * 16; const size_t off = (size_t)row * 1024 + c;
;                         const f32x4 v0 = acc[ai][bj][m][0] * rs[ai][m], v1 = acc[ai][bj][m][1] * rs[ai][m];
;                         const float v[8] = {v0[0], v0[1], v0[2], v0[3], v1[0], v1[1], v1[2], v1[3]};
;                         float y[8];
;                         if (region == 0) {
; #pragma unroll
;                             for (int j = 0; j < 8; ++j) y[j] = silu_f(v[j]);
;                             *(v4u*)(o0 + off) = pack8(y);
;                         } else if (region == 1) {
;                             float lf[8];
; #pragma unroll
;                             for (int j = 0; j < 8; ++j) {
;                                 const float om = 1.f - lb[j];
;                                 const float fc = fminf(fmaxf(v[j], -80.f), 80.f);
;                                 const float e = __expf(-fc), sg = __builtin_amdgcn_rcpf(1.f + e);
;                                 y[j] = om * e * sg;
;                                 lf[j] = __logf(fmaxf(lb[j] + om * sg, 1e-30f));
;                             }
;                             *(v4u*)(o1 + off) = pack8(y);
;                             *(f32x4*)(of + off) = (f32x4){lf[0], lf[1], lf[2], lf[3]}; *(f32x4*)(of + off + 4) = (f32x4){lf[4], lf[5], lf[6], lf[7]};
.LBB0_1063:
	v_mov_b32_e32 v93, v92
	v_mov_b32_e32 v30, v92
	v_mov_b32_e32 v31, v92
	v_or_b32_e32 v90, v90, v94
	v_pk_mul_f32 v[26:27], v[24:25], v[30:31]
	v_pk_mul_f32 v[28:29], v[22:23], v[92:93]
	v_pk_mul_f32 v[22:23], v[20:21], v[30:31]
	v_pk_mul_f32 v[24:25], v[18:19], v[92:93]
	s_and_b64 vcc, exec, s[44:45]
	s_mov_b64 s[0:1], -1
	s_cbranch_vccnz .LBB0_1072
	s_and_b64 vcc, exec, s[42:43]
	s_cbranch_vccnz .LBB0_1066
	v_max_f32_e32 v18, v28, v28
	s_mov_b32 s28, 0xc2a00000
	v_med3_f32 v18, v18, s28, v195
	v_mul_f32_e32 v18, 0xbfb8aa3b, v18
	v_exp_f32_e32 v18, v18
	v_pk_add_f32 v[32:33], v[72:73], 1.0 op_sel_hi:[1,0] neg_lo:[1,0] neg_hi:[1,0]
	s_mov_b32 s13, 0x3f317217
	s_mov_b32 s15, 0x7f800000
	v_add_f32_e32 v19, 1.0, v18
	v_rcp_f32_e32 v20, v19
	v_max_f32_e32 v19, v29, v29
	v_med3_f32 v19, v19, s28, v195
	v_mul_f32_e32 v19, 0xbfb8aa3b, v19
	v_exp_f32_e32 v19, v19
	v_pk_add_f32 v[36:37], v[70:71], 1.0 op_sel_hi:[1,0] neg_lo:[1,0] neg_hi:[1,0]
	v_pk_add_f32 v[38:39], v[68:69], 1.0 op_sel_hi:[1,0] neg_lo:[1,0] neg_hi:[1,0]
	v_pk_add_f32 v[42:43], v[66:67], 1.0 op_sel_hi:[1,0] neg_lo:[1,0] neg_hi:[1,0]
	v_add_f32_e32 v21, 1.0, v19
	v_rcp_f32_e32 v21, v21
	v_pk_mul_f32 v[18:19], v[18:19], v[32:33]
	s_nop 0
	v_pk_mul_f32 v[30:31], v[20:21], v[18:19]
	v_fma_f32 v18, v20, v32, v72
	v_max_f32_e32 v18, 0xda24260, v18
	v_cvt_pk_bf16_f32 v30, v30, v31
	s_nop 0
	v_log_f32_e32 v18, v18
	s_nop 0
	v_mul_f32_e32 v19, 0x3f317217, v18
	v_fma_f32 v19, v18, s13, -v19
	v_fmac_f32_e32 v19, 0x3377d1cf, v18
	v_fmac_f32_e32 v19, 0x3f317217, v18
	s_nop 1
	v_mov_b32_e32 v18, v19
	v_fma_f32 v19, v21, v33, v73
	v_max_f32_e32 v19, 0xda24260, v19
	s_nop 1
	v_log_f32_e32 v19, v19
	s_nop 0
	v_mul_f32_e32 v20, 0x3f317217, v19
	v_fma_f32 v20, v19, s13, -v20
	v_fmac_f32_e32 v20, 0x3377d1cf, v19
	v_fmac_f32_e32 v20, 0x3f317217, v19
	s_nop 1
	v_mov_b32_e32 v19, v20
	v_max_f32_e32 v20, v26, v26
	v_med3_f32 v20, v20, s28, v195
	v_mul_f32_e32 v20, 0xbfb8aa3b, v20
	v_exp_f32_e32 v20, v20
	s_nop 0
	v_add_f32_e32 v21, 1.0, v20
	v_rcp_f32_e32 v34, v21
	v_max_f32_e32 v21, v27, v27
	v_med3_f32 v21, v21, s28, v195
	v_mul_f32_e32 v21, 0xbfb8aa3b, v21
	v_exp_f32_e32 v21, v21
	s_nop 0
	v_add_f32_e32 v32, 1.0, v21
	v_rcp_f32_e32 v35, v32
	v_pk_mul_f32 v[20:21], v[20:21], v[36:37]
	s_nop 0
	v_pk_mul_f32 v[32:33], v[34:35], v[20:21]
	v_fma_f32 v20, v34, v36, v70
	v_max_f32_e32 v20, 0xda24260, v20
	v_cvt_pk_bf16_f32 v31, v32, v33
	s_nop 0
	v_log_f32_e32 v20, v20
	s_nop 0
	v_mul_f32_e32 v21, 0x3f317217, v20
	v_fma_f32 v21, v20, s13, -v21
	v_fmac_f32_e32 v21, 0x3377d1cf, v20
	v_fmac_f32_e32 v21, 0x3f317217, v20
	s_nop 1
	v_mov_b32_e32 v20, v21
	v_fma_f32 v21, v35, v37, v71
	v_max_f32_e32 v21, 0xda24260, v21
	s_nop 1
	v_log_f32_e32 v21, v21
	s_nop 0
	v_mul_f32_e32 v34, 0x3f317217, v21
	v_fma_f32 v34, v21, s13, -v34
	v_fmac_f32_e32 v34, 0x3377d1cf, v21
	v_fmac_f32_e32 v34, 0x3f317217, v21
	s_nop 1
	v_mov_b32_e32 v21, v34
	v_max_f32_e32 v34, v24, v24
	v_med3_f32 v34, v34, s28, v195
	v_mul_f32_e32 v34, 0xbfb8aa3b, v34
	v_exp_f32_e32 v34, v34
	s_nop 0
	v_add_f32_e32 v35, 1.0, v34
	v_rcp_f32_e32 v36, v35
	v_max_f32_e32 v35, v25, v25
	v_med3_f32 v35, v35, s28, v195
	v_mul_f32_e32 v35, 0xbfb8aa3b, v35
	v_exp_f32_e32 v35, v35
	s_nop 0
	v_add_f32_e32 v37, 1.0, v35
	v_rcp_f32_e32 v37, v37
	v_pk_mul_f32 v[34:35], v[34:35], v[38:39]
	s_nop 0
	v_pk_mul_f32 v[40:41], v[36:37], v[34:35]
	v_fma_f32 v34, v36, v38, v68
	v_max_f32_e32 v34, 0xda24260, v34
	v_cvt_pk_bf16_f32 v32, v40, v41
	s_nop 0
	v_log_f32_e32 v34, v34
	s_nop 0
	v_mul_f32_e32 v35, 0x3f317217, v34
	v_fma_f32 v35, v34, s13, -v35
	v_fmac_f32_e32 v35, 0x3377d1cf, v34
	v_fmac_f32_e32 v35, 0x3f317217, v34
	s_nop 1
	v_mov_b32_e32 v34, v35
	v_fma_f32 v35, v37, v39, v69
	v_max_f32_e32 v35, 0xda24260, v35
	s_nop 1
	v_log_f32_e32 v35, v35
	s_nop 0
	v_mul_f32_e32 v36, 0x3f317217, v35
	v_fma_f32 v36, v35, s13, -v36
	v_fmac_f32_e32 v36, 0x3377d1cf, v35
	v_fmac_f32_e32 v36, 0x3f317217, v35
	s_nop 1
	v_mov_b32_e32 v35, v36
	v_max_f32_e32 v36, v22, v22
	v_med3_f32 v36, v36, s28, v195
	v_mul_f32_e32 v36, 0xbfb8aa3b, v36
	v_exp_f32_e32 v36, v36
	s_nop 0
	v_add_f32_e32 v37, 1.0, v36
	v_rcp_f32_e32 v38, v37
	v_max_f32_e32 v37, v23, v23
	v_med3_f32 v37, v37, s28, v195
	v_mul_f32_e32 v37, 0xbfb8aa3b, v37
	v_exp_f32_e32 v37, v37
	s_nop 0
	v_add_f32_e32 v39, 1.0, v37
	v_rcp_f32_e32 v39, v39
	v_pk_mul_f32 v[36:37], v[36:37], v[42:43]
	s_nop 0
	v_pk_mul_f32 v[44:45], v[38:39], v[36:37]
	v_fma_f32 v36, v38, v42, v66
	v_max_f32_e32 v36, 0xda24260, v36
	v_cvt_pk_bf16_f32 v33, v44, v45
	s_nop 0
	v_log_f32_e32 v36, v36
	s_nop 0
	v_mul_f32_e32 v37, 0x3f317217, v36
	v_fma_f32 v37, v36, s13, -v37
	v_fmac_f32_e32 v37, 0x3377d1cf, v36
	v_fmac_f32_e32 v37, 0x3f317217, v36
	s_nop 1
	v_mov_b32_e32 v36, v37
	v_fma_f32 v37, v39, v43, v67
	v_max_f32_e32 v37, 0xda24260, v37
	s_nop 1
	v_log_f32_e32 v37, v37
	s_nop 0
	v_mul_f32_e32 v38, 0x3f317217, v37
	v_fma_f32 v38, v37, s13, -v38
	v_fmac_f32_e32 v38, 0x3377d1cf, v37
	v_fmac_f32_e32 v38, 0x3f317217, v37
	s_nop 1
	v_mov_b32_e32 v37, v38
	v_readlane_b32 s0, v253, 0
	v_readlane_b32 s1, v253, 1
	s_nop 0
	v_lshl_add_u64 v[38:39], v[90:91], 1, s[0:1]
	global_store_dwordx4 v[38:39], v[30:33], off
	s_mov_b64 s[0:1], 0
	s_nop 0
	v_lshl_add_u64 v[30:31], v[90:91], 2, s[2:3]
	global_store_dwordx4 v[30:31], v[18:21], off
	global_store_dwordx4 v[30:31], v[34:37], off offset:16

; __device__ __forceinline__ float silu_f(float x) { return x * __builtin_amdgcn_rcpf(1.f + __expf(-x)); }
; __device__ __forceinline__ v4u pack8(const float (&y)[8]) { return (v4u){pk2(y[0], y[1]), pk2(y[2], y[3]), pk2(y[4], y[5]), pk2(y[6], y[7])}; }
;     __device__ __forceinline__ void operator()(const f32x4 (&acc)[2][2][4][2], const pg8::Unit& u, int wr, int wc, int fr, int fq) const {
;     ...
;                         const int row = lrow0 + ai * 128 + m * 16; const size_t off = (size_t)row * 1024 + c;
;                         const f32x4 v0 = acc[ai][bj][m][0] * rs[ai][m], v1 = acc[ai][bj][m][1] * rs[ai][m];
;                         const float v[8] = {v0[0], v0[1], v0[2], v0[3], v1[0], v1[1], v1[2], v1[3]};
;                         float y[8];
;                         if (region == 0) {
; #pragma unroll
;                             for (int j = 0; j < 8; ++j) y[j] = silu_f(v[j]);
;                             *(v4u*)(o0 + off) = pack8(y);
;                         } else if (region == 1) {
;                             float lf[8];
; #pragma unroll
;                             for (int j = 0; j < 8; ++j) {
;                                 const float om = 1.f - lb[j];
;                                 const float fc = fminf(fmaxf(v[j], -80.f), 80.f);
;                                 const float e = __expf(-fc), sg = __builtin_amdgcn_rcpf(1.f + e);
;                                 y[j] = om * e * sg;
;                                 lf[j] = __logf(fmaxf(lb[j] + om * sg, 1e-30f));
;                             }
;                             *(v4u*)(o1 + off) = pack8(y);
;                             *(f32x4*)(of + off) = (f32x4){lf[0], lf[1], lf[2], lf[3]}; *(f32x4*)(of + off + 4) = (f32x4){lf[4], lf[5], lf[6], lf[7]};
.LBB0_1074:
	v_mov_b32_e32 v85, v84
	v_mov_b32_e32 v22, v84
	v_mov_b32_e32 v23, v84
	v_or_b32_e32 v82, v82, v94
	v_pk_mul_f32 v[18:19], v[16:17], v[22:23]
	v_pk_mul_f32 v[20:21], v[14:15], v[84:85]
	v_pk_mul_f32 v[14:15], v[12:13], v[22:23]
	v_pk_mul_f32 v[16:17], v[10:11], v[84:85]
	s_and_b64 vcc, exec, s[44:45]
	s_mov_b64 s[0:1], -1
	s_cbranch_vccnz .LBB0_1083
	s_and_b64 vcc, exec, s[42:43]
	s_cbranch_vccnz .LBB0_1077
	v_max_f32_e32 v10, v20, v20
	s_mov_b32 s28, 0xc2a00000
	v_med3_f32 v10, v10, s28, v195
	v_mul_f32_e32 v10, 0xbfb8aa3b, v10
	v_exp_f32_e32 v10, v10
	v_pk_add_f32 v[24:25], v[72:73], 1.0 op_sel_hi:[1,0] neg_lo:[1,0] neg_hi:[1,0]
	s_mov_b32 s13, 0x3f317217
	s_mov_b32 s15, 0x7f800000
	v_add_f32_e32 v11, 1.0, v10
	v_rcp_f32_e32 v12, v11
	v_max_f32_e32 v11, v21, v21
	v_med3_f32 v11, v11, s28, v195
	v_mul_f32_e32 v11, 0xbfb8aa3b, v11
	v_exp_f32_e32 v11, v11
	v_pk_add_f32 v[28:29], v[70:71], 1.0 op_sel_hi:[1,0] neg_lo:[1,0] neg_hi:[1,0]
	v_pk_add_f32 v[30:31], v[68:69], 1.0 op_sel_hi:[1,0] neg_lo:[1,0] neg_hi:[1,0]
	v_pk_add_f32 v[34:35], v[66:67], 1.0 op_sel_hi:[1,0] neg_lo:[1,0] neg_hi:[1,0]
	v_add_f32_e32 v13, 1.0, v11
	v_rcp_f32_e32 v13, v13
	v_pk_mul_f32 v[10:11], v[10:11], v[24:25]
	s_nop 0
	v_pk_mul_f32 v[22:23], v[12:13], v[10:11]
	v_fma_f32 v10, v12, v24, v72
	v_max_f32_e32 v10, 0xda24260, v10
	v_cvt_pk_bf16_f32 v22, v22, v23
	s_nop 0
	v_log_f32_e32 v10, v10
	s_nop 0
	v_mul_f32_e32 v11, 0x3f317217, v10
	v_fma_f32 v11, v10, s13, -v11
	v_fmac_f32_e32 v11, 0x3377d1cf, v10
	v_fmac_f32_e32 v11, 0x3f317217, v10
	s_nop 1
	v_mov_b32_e32 v10, v11
	v_fma_f32 v11, v13, v25, v73
	v_max_f32_e32 v11, 0xda24260, v11
	s_nop 1
	v_log_f32_e32 v11, v11
	s_nop 0
	v_mul_f32_e32 v12, 0x3f317217, v11
	v_fma_f32 v12, v11, s13, -v12
	v_fmac_f32_e32 v12, 0x3377d1cf, v11
	v_fmac_f32_e32 v12, 0x3f317217, v11
	s_nop 1
	v_mov_b32_e32 v11, v12
	v_max_f32_e32 v12, v18, v18
	v_med3_f32 v12, v12, s28, v195
	v_mul_f32_e32 v12, 0xbfb8aa3b, v12
	v_exp_f32_e32 v12, v12
	s_nop 0
	v_add_f32_e32 v13, 1.0, v12
	v_rcp_f32_e32 v26, v13
	v_max_f32_e32 v13, v19, v19
	v_med3_f32 v13, v13, s28, v195
	v_mul_f32_e32 v13, 0xbfb8aa3b, v13
	v_exp_f32_e32 v13, v13
	s_nop 0
	v_add_f32_e32 v24, 1.0, v13
	v_rcp_f32_e32 v27, v24
	v_pk_mul_f32 v[12:13], v[12:13], v[28:29]
	s_nop 0
	v_pk_mul_f32 v[24:25], v[26:27], v[12:13]
	v_fma_f32 v12, v26, v28, v70
	v_max_f32_e32 v12, 0xda24260, v12
	v_cvt_pk_bf16_f32 v23, v24, v25
	s_nop 0
	v_log_f32_e32 v12, v12
	s_nop 0
	v_mul_f32_e32 v13, 0x3f317217, v12
	v_fma_f32 v13, v12, s13, -v13
	v_fmac_f32_e32 v13, 0x3377d1cf, v12
	v_fmac_f32_e32 v13, 0x3f317217, v12
	s_nop 1
	v_mov_b32_e32 v12, v13
	v_fma_f32 v13, v27, v29, v71
	v_max_f32_e32 v13, 0xda24260, v13
	s_nop 1
	v_log_f32_e32 v13, v13
	s_nop 0
	v_mul_f32_e32 v26, 0x3f317217, v13
	v_fma_f32 v26, v13, s13, -v26
	v_fmac_f32_e32 v26, 0x3377d1cf, v13
	v_fmac_f32_e32 v26, 0x3f317217, v13
	s_nop 1
	v_mov_b32_e32 v13, v26
	v_max_f32_e32 v26, v16, v16
	v_med3_f32 v26, v26, s28, v195
	v_mul_f32_e32 v26, 0xbfb8aa3b, v26
	v_exp_f32_e32 v26, v26
	s_nop 0
	v_add_f32_e32 v27, 1.0, v26
	v_rcp_f32_e32 v28, v27
	v_max_f32_e32 v27, v17, v17
	v_med3_f32 v27, v27, s28, v195
	v_mul_f32_e32 v27, 0xbfb8aa3b, v27
	v_exp_f32_e32 v27, v27
	s_nop 0
	v_add_f32_e32 v29, 1.0, v27
	v_rcp_f32_e32 v29, v29
	v_pk_mul_f32 v[26:27], v[26:27], v[30:31]
	s_nop 0
	v_pk_mul_f32 v[32:33], v[28:29], v[26:27]
	v_fma_f32 v26, v28, v30, v68
	v_max_f32_e32 v26, 0xda24260, v26
	v_cvt_pk_bf16_f32 v24, v32, v33
	s_nop 0
	v_log_f32_e32 v26, v26
	s_nop 0
	v_mul_f32_e32 v27, 0x3f317217, v26
	v_fma_f32 v27, v26, s13, -v27
	v_fmac_f32_e32 v27, 0x3377d1cf, v26
	v_fmac_f32_e32 v27, 0x3f317217, v26
	s_nop 1
	v_mov_b32_e32 v26, v27
	v_fma_f32 v27, v29, v31, v69
	v_max_f32_e32 v27, 0xda24260, v27
	s_nop 1
	v_log_f32_e32 v27, v27
	s_nop 0
	v_mul_f32_e32 v28, 0x3f317217, v27
	v_fma_f32 v28, v27, s13, -v28
	v_fmac_f32_e32 v28, 0x3377d1cf, v27
	v_fmac_f32_e32 v28, 0x3f317217, v27
	s_nop 1
	v_mov_b32_e32 v27, v28
	v_max_f32_e32 v28, v14, v14
	v_med3_f32 v28, v28, s28, v195
	v_mul_f32_e32 v28, 0xbfb8aa3b, v28
	v_exp_f32_e32 v28, v28
	s_nop 0
	v_add_f32_e32 v29, 1.0, v28
	v_rcp_f32_e32 v30, v29
	v_max_f32_e32 v29, v15, v15
	v_med3_f32 v29, v29, s28, v195
	v_mul_f32_e32 v29, 0xbfb8aa3b, v29
	v_exp_f32_e32 v29, v29
	s_nop 0
	v_add_f32_e32 v31, 1.0, v29
	v_rcp_f32_e32 v31, v31
	v_pk_mul_f32 v[28:29], v[28:29], v[34:35]
	s_nop 0
	v_pk_mul_f32 v[36:37], v[30:31], v[28:29]
	v_fma_f32 v28, v30, v34, v66
	v_max_f32_e32 v28, 0xda24260, v28
	v_cvt_pk_bf16_f32 v25, v36, v37
	s_nop 0
	v_log_f32_e32 v28, v28
	s_nop 0
	v_mul_f32_e32 v29, 0x3f317217, v28
	v_fma_f32 v29, v28, s13, -v29
	v_fmac_f32_e32 v29, 0x3377d1cf, v28
	v_fmac_f32_e32 v29, 0x3f317217, v28
	s_nop 1
	v_mov_b32_e32 v28, v29
	v_fma_f32 v29, v31, v35, v67
	v_max_f32_e32 v29, 0xda24260, v29
	s_nop 1
	v_log_f32_e32 v29, v29
	s_nop 0
	v_mul_f32_e32 v30, 0x3f317217, v29
	v_fma_f32 v30, v29, s13, -v30
	v_fmac_f32_e32 v30, 0x3377d1cf, v29
	v_fmac_f32_e32 v30, 0x3f317217, v29
	s_nop 1
	v_mov_b32_e32 v29, v30
	v_readlane_b32 s0, v253, 0
	v_readlane_b32 s1, v253, 1
	s_nop 0
	v_lshl_add_u64 v[30:31], v[82:83], 1, s[0:1]
	global_store_dwordx4 v[30:31], v[22:25], off
	s_mov_b64 s[0:1], 0
	s_nop 0
	v_lshl_add_u64 v[22:23], v[82:83], 2, s[2:3]
	global_store_dwordx4 v[22:23], v[10:13], off
	global_store_dwordx4 v[22:23], v[26:29], off offset:16
